# F epilogue load batches software-pipelined as well (on top of pipelined G/J epilogue, local barriers, qk rewrite)
# speedup vs baseline: 1.0024x; 1.0024x over previous
; DI unsigned pk2(float a, float b) { f32x2 v = {a, b}; bf2_t r = __builtin_convertvector(v, bf2_t); return __builtin_bit_cast(unsigned, r); }
; DI float bf_lo(unsigned u) { return __uint_as_float(u << 16); }
; DI float bf_hi(unsigned u) { return __uint_as_float(u & 0xffff0000u); }
; DI void gemm_up_pass_big(const bf16_t* Y, const bf16_t* W, const bf16_t* __restrict__ GBR, int gcol0, bf16_t* __restrict__ MG, bool first,
;                          int mt, int nt, char* smem) {
;     ...
;     const int r = tid >> 4, ch = tid & 15;
; #pragma unroll 2
;     for (int ps = 0; ps < 8; ++ps) {
;       const int row = ps * 16 + r;
;       const float4 a0 = *(const float4*)(st + row * 132 + ch * 8), a1 = *(const float4*)(st + row * 132 + ch * 8 + 4);
;       const size_t grow = (size_t)(m0 + h * 128 + row);
;       const u32x4 gv = *(const u32x4*)(GBR + grow * 2048 + gcol0 + n0 + ch * 8);
;       float v[8];
;       v[0] = bf_lo(gv.x) * a0.x; v[1] = bf_hi(gv.x) * a0.y; v[2] = bf_lo(gv.y) * a0.z; v[3] = bf_hi(gv.y) * a0.w;
;       v[4] = bf_lo(gv.z) * a1.x; v[5] = bf_hi(gv.z) * a1.y; v[6] = bf_lo(gv.w) * a1.z; v[7] = bf_hi(gv.w) * a1.w;
;       bf16_t* mp = MG + grow * 1024 + n0 + ch * 8;
;       if (!first) {
;         const u32x4 pv = *(const u32x4*)mp;
;         v[0] += bf_lo(pv.x); v[1] += bf_hi(pv.x); v[2] += bf_lo(pv.y); v[3] += bf_hi(pv.y);
;         v[4] += bf_lo(pv.z); v[5] += bf_hi(pv.z); v[6] += bf_lo(pv.w); v[7] += bf_hi(pv.w);
;       }
;       u32x4 ov; ov.x = pk2(v[0], v[1]); ov.y = pk2(v[2], v[3]); ov.z = pk2(v[4], v[5]); ov.w = pk2(v[6], v[7]);
;       *(u32x4*)mp = ov;
;     }
.LBB0_1047:
	v_lshl_add_u64 v[194:195], v[136:137], 0, s[28:29]
	v_lshl_add_u64 v[196:197], v[132:133], 0, s[28:29]
	v_lshl_add_u64 v[202:203], v[134:135], 0, s[28:29]
	v_lshl_add_u64 v[204:205], v[130:131], 0, s[28:29]
	global_load_dwordx4 v[138:141], v[194:195], off
	v_lshl_add_u64 v[194:195], v[194:195], 0, s[92:93]
	global_load_dwordx4 v[142:145], v[196:197], off
	v_lshl_add_u64 v[196:197], v[196:197], 0, s[92:93]
	global_load_dwordx4 v[146:149], v[194:195], off
	v_lshl_add_u64 v[194:195], v[194:195], 0, s[92:93]
	global_load_dwordx4 v[150:153], v[196:197], off
	v_lshl_add_u64 v[196:197], v[196:197], 0, s[92:93]
	ds_read_b128 v[172:175], v0 offset:0
	ds_read_b128 v[176:179], v0 offset:16
	s_waitcnt vmcnt(3) lgkmcnt(0)
	v_lshlrev_b32_e32 v190, 16, v138
	v_and_b32_e32 v191, 0xffff0000, v138
	v_pk_mul_f32 v[172:173], v[172:173], v[190:191]
	v_lshlrev_b32_e32 v190, 16, v139
	v_and_b32_e32 v191, 0xffff0000, v139
	v_pk_mul_f32 v[174:175], v[174:175], v[190:191]
	v_lshlrev_b32_e32 v190, 16, v140
	v_and_b32_e32 v191, 0xffff0000, v140
	v_pk_mul_f32 v[176:177], v[176:177], v[190:191]
	v_lshlrev_b32_e32 v190, 16, v141
	v_and_b32_e32 v191, 0xffff0000, v141
	v_pk_mul_f32 v[178:179], v[178:179], v[190:191]
	v_cvt_pk_bf16_f32 v186, v172, v173
	v_cvt_pk_bf16_f32 v187, v174, v175
	v_cvt_pk_bf16_f32 v188, v176, v177
	v_cvt_pk_bf16_f32 v189, v178, v179
	global_store_dwordx4 v[202:203], v[186:189], off
	s_nop 1
	v_lshl_add_u64 v[202:203], v[202:203], 0, s[38:39]
	global_load_dwordx4 v[138:141], v[194:195], off
	v_lshl_add_u64 v[194:195], v[194:195], 0, s[92:93]
	ds_read_b128 v[172:175], v0 offset:8448
	ds_read_b128 v[176:179], v0 offset:8464
	s_waitcnt vmcnt(4) lgkmcnt(0)
	v_lshlrev_b32_e32 v190, 16, v142
	v_and_b32_e32 v191, 0xffff0000, v142
	v_pk_mul_f32 v[172:173], v[172:173], v[190:191]
	v_lshlrev_b32_e32 v190, 16, v143
	v_and_b32_e32 v191, 0xffff0000, v143
	v_pk_mul_f32 v[174:175], v[174:175], v[190:191]
	v_lshlrev_b32_e32 v190, 16, v144
	v_and_b32_e32 v191, 0xffff0000, v144
	v_pk_mul_f32 v[176:177], v[176:177], v[190:191]
	v_lshlrev_b32_e32 v190, 16, v145
	v_and_b32_e32 v191, 0xffff0000, v145
	v_pk_mul_f32 v[178:179], v[178:179], v[190:191]
	v_cvt_pk_bf16_f32 v186, v172, v173
	v_cvt_pk_bf16_f32 v187, v174, v175
	v_cvt_pk_bf16_f32 v188, v176, v177
	v_cvt_pk_bf16_f32 v189, v178, v179
	global_store_dwordx4 v[204:205], v[186:189], off
	s_nop 1
	v_lshl_add_u64 v[204:205], v[204:205], 0, s[38:39]
	global_load_dwordx4 v[142:145], v[196:197], off
	v_lshl_add_u64 v[196:197], v[196:197], 0, s[92:93]
	ds_read_b128 v[172:175], v0 offset:16896
	ds_read_b128 v[176:179], v0 offset:16912
	s_waitcnt vmcnt(5) lgkmcnt(0)
	v_lshlrev_b32_e32 v190, 16, v146
	v_and_b32_e32 v191, 0xffff0000, v146
	v_pk_mul_f32 v[172:173], v[172:173], v[190:191]
	v_lshlrev_b32_e32 v190, 16, v147
	v_and_b32_e32 v191, 0xffff0000, v147
	v_pk_mul_f32 v[174:175], v[174:175], v[190:191]
	v_lshlrev_b32_e32 v190, 16, v148
	v_and_b32_e32 v191, 0xffff0000, v148
	v_pk_mul_f32 v[176:177], v[176:177], v[190:191]
	v_lshlrev_b32_e32 v190, 16, v149
	v_and_b32_e32 v191, 0xffff0000, v149
	v_pk_mul_f32 v[178:179], v[178:179], v[190:191]
	v_cvt_pk_bf16_f32 v186, v172, v173
	v_cvt_pk_bf16_f32 v187, v174, v175
	v_cvt_pk_bf16_f32 v188, v176, v177
	v_cvt_pk_bf16_f32 v189, v178, v179
	global_store_dwordx4 v[202:203], v[186:189], off
	s_nop 1
	v_lshl_add_u64 v[202:203], v[202:203], 0, s[38:39]
	global_load_dwordx4 v[146:149], v[194:195], off
	v_lshl_add_u64 v[194:195], v[194:195], 0, s[92:93]
	ds_read_b128 v[172:175], v0 offset:25344
	ds_read_b128 v[176:179], v0 offset:25360
	s_waitcnt vmcnt(6) lgkmcnt(0)
	v_lshlrev_b32_e32 v190, 16, v150
	v_and_b32_e32 v191, 0xffff0000, v150
	v_pk_mul_f32 v[172:173], v[172:173], v[190:191]
	v_lshlrev_b32_e32 v190, 16, v151
	v_and_b32_e32 v191, 0xffff0000, v151
	v_pk_mul_f32 v[174:175], v[174:175], v[190:191]
	v_lshlrev_b32_e32 v190, 16, v152
	v_and_b32_e32 v191, 0xffff0000, v152
	v_pk_mul_f32 v[176:177], v[176:177], v[190:191]
	v_lshlrev_b32_e32 v190, 16, v153
	v_and_b32_e32 v191, 0xffff0000, v153
	v_pk_mul_f32 v[178:179], v[178:179], v[190:191]
	v_cvt_pk_bf16_f32 v186, v172, v173
	v_cvt_pk_bf16_f32 v187, v174, v175
	v_cvt_pk_bf16_f32 v188, v176, v177
	v_cvt_pk_bf16_f32 v189, v178, v179
	global_store_dwordx4 v[204:205], v[186:189], off
	s_nop 1
	v_lshl_add_u64 v[204:205], v[204:205], 0, s[38:39]
	global_load_dwordx4 v[150:153], v[196:197], off
	v_lshl_add_u64 v[196:197], v[196:197], 0, s[92:93]
	ds_read_b128 v[172:175], v0 offset:33792
	ds_read_b128 v[176:179], v0 offset:33808
	s_waitcnt vmcnt(6) lgkmcnt(0)
	v_lshlrev_b32_e32 v190, 16, v138
	v_and_b32_e32 v191, 0xffff0000, v138
	v_pk_mul_f32 v[172:173], v[172:173], v[190:191]
	v_lshlrev_b32_e32 v190, 16, v139
	v_and_b32_e32 v191, 0xffff0000, v139
	v_pk_mul_f32 v[174:175], v[174:175], v[190:191]
	v_lshlrev_b32_e32 v190, 16, v140
	v_and_b32_e32 v191, 0xffff0000, v140
	v_pk_mul_f32 v[176:177], v[176:177], v[190:191]
	v_lshlrev_b32_e32 v190, 16, v141
	v_and_b32_e32 v191, 0xffff0000, v141
	v_pk_mul_f32 v[178:179], v[178:179], v[190:191]
	v_cvt_pk_bf16_f32 v186, v172, v173
	v_cvt_pk_bf16_f32 v187, v174, v175
	v_cvt_pk_bf16_f32 v188, v176, v177
	v_cvt_pk_bf16_f32 v189, v178, v179
	global_store_dwordx4 v[202:203], v[186:189], off
	s_nop 1
	v_lshl_add_u64 v[202:203], v[202:203], 0, s[38:39]
	ds_read_b128 v[172:175], v0 offset:42240
	ds_read_b128 v[176:179], v0 offset:42256
	s_waitcnt vmcnt(5) lgkmcnt(0)
; DI unsigned pk2(float a, float b) { f32x2 v = {a, b}; bf2_t r = __builtin_convertvector(v, bf2_t); return __builtin_bit_cast(unsigned, r); }
; DI float bf_lo(unsigned u) { return __uint_as_float(u << 16); }
; DI float bf_hi(unsigned u) { return __uint_as_float(u & 0xffff0000u); }
; DI void stage_half(float* st, const f32x16 (&acc)[4][2], int h, int tid) {
;   const int lane = tid & 63, w = tid >> 6, wm = w >> 1, wn = w & 1, c = lane & 31, half = lane >> 5;
;   if (wm == h) {
; DI void gemm_up_pass_big(const bf16_t* Y, const bf16_t* W, const bf16_t* __restrict__ GBR, int gcol0, bf16_t* __restrict__ MG, bool first,
;                          int mt, int nt, char* smem) {
;     ...
;     for (int ps = 0; ps < 8; ++ps) {
;       const int row = ps * 16 + r;
;       const float4 a0 = *(const float4*)(st + row * 132 + ch * 8), a1 = *(const float4*)(st + row * 132 + ch * 8 + 4);
;       const size_t grow = (size_t)(m0 + h * 128 + row);
;       const u32x4 gv = *(const u32x4*)(GBR + grow * 2048 + gcol0 + n0 + ch * 8);
;       float v[8];
;       v[0] = bf_lo(gv.x) * a0.x; v[1] = bf_hi(gv.x) * a0.y; v[2] = bf_lo(gv.y) * a0.z; v[3] = bf_hi(gv.y) * a0.w;
;       v[4] = bf_lo(gv.z) * a1.x; v[5] = bf_hi(gv.z) * a1.y; v[6] = bf_lo(gv.w) * a1.z; v[7] = bf_hi(gv.w) * a1.w;
;       bf16_t* mp = MG + grow * 1024 + n0 + ch * 8;
;       if (!first) {
;         const u32x4 pv = *(const u32x4*)mp;
;         v[0] += bf_lo(pv.x); v[1] += bf_hi(pv.x); v[2] += bf_lo(pv.y); v[3] += bf_hi(pv.y);
;         v[4] += bf_lo(pv.z); v[5] += bf_hi(pv.z); v[6] += bf_lo(pv.w); v[7] += bf_hi(pv.w);
;       }
;       u32x4 ov; ov.x = pk2(v[0], v[1]); ov.y = pk2(v[2], v[3]); ov.z = pk2(v[4], v[5]); ov.w = pk2(v[6], v[7]);
;       *(u32x4*)mp = ov;
;     }
;     __syncthreads();
	v_lshlrev_b32_e32 v190, 16, v142
	v_and_b32_e32 v191, 0xffff0000, v142
	v_pk_mul_f32 v[172:173], v[172:173], v[190:191]
	v_lshlrev_b32_e32 v190, 16, v143
	v_and_b32_e32 v191, 0xffff0000, v143
	v_pk_mul_f32 v[174:175], v[174:175], v[190:191]
	v_lshlrev_b32_e32 v190, 16, v144
	v_and_b32_e32 v191, 0xffff0000, v144
	v_pk_mul_f32 v[176:177], v[176:177], v[190:191]
	v_lshlrev_b32_e32 v190, 16, v145
	v_and_b32_e32 v191, 0xffff0000, v145
	v_pk_mul_f32 v[178:179], v[178:179], v[190:191]
	v_cvt_pk_bf16_f32 v186, v172, v173
	v_cvt_pk_bf16_f32 v187, v174, v175
	v_cvt_pk_bf16_f32 v188, v176, v177
	v_cvt_pk_bf16_f32 v189, v178, v179
	global_store_dwordx4 v[204:205], v[186:189], off
	s_nop 1
	v_lshl_add_u64 v[204:205], v[204:205], 0, s[38:39]
	ds_read_b128 v[172:175], v0 offset:50688
	ds_read_b128 v[176:179], v0 offset:50704
	s_waitcnt vmcnt(4) lgkmcnt(0)
	v_lshlrev_b32_e32 v190, 16, v146
	v_and_b32_e32 v191, 0xffff0000, v146
	v_pk_mul_f32 v[172:173], v[172:173], v[190:191]
	v_lshlrev_b32_e32 v190, 16, v147
	v_and_b32_e32 v191, 0xffff0000, v147
	v_pk_mul_f32 v[174:175], v[174:175], v[190:191]
	v_lshlrev_b32_e32 v190, 16, v148
	v_and_b32_e32 v191, 0xffff0000, v148
	v_pk_mul_f32 v[176:177], v[176:177], v[190:191]
	v_lshlrev_b32_e32 v190, 16, v149
	v_and_b32_e32 v191, 0xffff0000, v149
	v_pk_mul_f32 v[178:179], v[178:179], v[190:191]
	v_cvt_pk_bf16_f32 v186, v172, v173
	v_cvt_pk_bf16_f32 v187, v174, v175
	v_cvt_pk_bf16_f32 v188, v176, v177
	v_cvt_pk_bf16_f32 v189, v178, v179
	global_store_dwordx4 v[202:203], v[186:189], off
	s_nop 1
	v_lshl_add_u64 v[202:203], v[202:203], 0, s[38:39]
	ds_read_b128 v[172:175], v0 offset:59136
	ds_read_b128 v[176:179], v0 offset:59152
	s_waitcnt vmcnt(3) lgkmcnt(0)
	v_lshlrev_b32_e32 v190, 16, v150
	v_and_b32_e32 v191, 0xffff0000, v150
	v_pk_mul_f32 v[172:173], v[172:173], v[190:191]
	v_lshlrev_b32_e32 v190, 16, v151
	v_and_b32_e32 v191, 0xffff0000, v151
	v_pk_mul_f32 v[174:175], v[174:175], v[190:191]
	v_lshlrev_b32_e32 v190, 16, v152
	v_and_b32_e32 v191, 0xffff0000, v152
	v_pk_mul_f32 v[176:177], v[176:177], v[190:191]
	v_lshlrev_b32_e32 v190, 16, v153
	v_and_b32_e32 v191, 0xffff0000, v153
	v_pk_mul_f32 v[178:179], v[178:179], v[190:191]
	v_cvt_pk_bf16_f32 v186, v172, v173
	v_cvt_pk_bf16_f32 v187, v174, v175
	v_cvt_pk_bf16_f32 v188, v176, v177
	v_cvt_pk_bf16_f32 v189, v178, v179
	global_store_dwordx4 v[204:205], v[186:189], off
	s_nop 1
	v_lshl_add_u64 v[204:205], v[204:205], 0, s[38:39]
	v_mov_b32_e32 v0, v216
	s_barrier
	s_nop 0
	v_and_b32_e32 v130, 0xffffff80, v0
	v_cmp_eq_u32_e32 vcc, s31, v130
	s_and_saveexec_b64 s[42:43], vcc
	s_cbranch_execz .LBB0_1050
; DI int crow(int i, int h) { return (i & 3) + 8 * (i >> 2) + 4 * h; }
; DI void stage_half(float* st, const f32x16 (&acc)[4][2], int h, int tid) {
;   const int lane = tid & 63, w = tid >> 6, wm = w >> 1, wn = w & 1, c = lane & 31, half = lane >> 5;
;   if (wm == h) {
; #pragma unroll
;     for (int mf = 0; mf < 4; ++mf)
; #pragma unroll
;       for (int nf = 0; nf < 2; ++nf)
; #pragma unroll
;         for (int i = 0; i < 16; ++i) st[(mf * 32 + crow(i, half)) * 132 + wn * 64 + nf * 32 + c] = acc[mf][nf][i];
;   }
; }
	v_lshrrev_b32_e32 v130, 3, v0
	v_and_b32_e32 v130, 4, v130
	v_and_b32_e32 v131, 0x5f, v0
	v_mul_u32_u24_e32 v130, 0x210, v130
	v_lshl_add_u32 v130, v131, 2, v130
	ds_write2_b32 v130, v98, v114 offset1:32
	ds_write2_b32 v130, v99, v115 offset0:132 offset1:164
	v_add_u32_e32 v98, 0x400, v130
	ds_write2_b32 v98, v100, v116 offset0:8 offset1:40
	ds_write2_b32 v98, v101, v117 offset0:140 offset1:172
	v_add_u32_e32 v98, 0x1000, v130
	ds_write2_b32 v98, v102, v118 offset0:32 offset1:64
	ds_write2_b32 v98, v103, v119 offset0:164 offset1:196
	v_add_u32_e32 v98, 0x1400, v130
	ds_write2_b32 v98, v104, v120 offset0:40 offset1:72
	ds_write2_b32 v98, v105, v121 offset0:172 offset1:204
	v_add_u32_e32 v98, 0x2000, v130
	ds_write2_b32 v98, v106, v122 offset0:64 offset1:96
	ds_write2_b32 v98, v107, v123 offset0:196 offset1:228
	v_add_u32_e32 v98, 0x2400, v130
	ds_write2_b32 v98, v108, v124 offset0:72 offset1:104
	ds_write2_b32 v98, v109, v125 offset0:204 offset1:236
	v_add_u32_e32 v98, 0x3000, v130
	ds_write2_b32 v98, v110, v126 offset0:96 offset1:128
	v_add_u32_e32 v98, 0x3200, v130
	ds_write2_b32 v98, v111, v127 offset0:100 offset1:132
	v_add_u32_e32 v98, 0x3400, v130
	ds_write2_b32 v98, v112, v128 offset0:104 offset1:136
	v_add_u32_e32 v98, 0x3600, v130
	ds_write2_b32 v98, v113, v129 offset0:108 offset1:140
	v_add_u32_e32 v98, 0x4000, v130
	ds_write2_b32 v98, v66, v82 offset0:128 offset1:160
	v_add_u32_e32 v66, 0x4400, v130
	ds_write2_b32 v66, v67, v83 offset0:4 offset1:36
	ds_write2_b32 v66, v68, v84 offset0:136 offset1:168
	v_add_u32_e32 v66, 0x4800, v130
	ds_write2_b32 v66, v69, v85 offset0:12 offset1:44
	v_add_u32_e32 v66, 0x5000, v130
	ds_write2_b32 v66, v70, v86 offset0:160 offset1:192
	v_add_u32_e32 v66, 0x5400, v130
	ds_write2_b32 v66, v71, v87 offset0:36 offset1:68
	ds_write2_b32 v66, v72, v88 offset0:168 offset1:200
	v_add_u32_e32 v66, 0x5800, v130
	ds_write2_b32 v66, v73, v89 offset0:44 offset1:76
	v_add_u32_e32 v66, 0x6000, v130
	ds_write2_b32 v66, v74, v90 offset0:192 offset1:224
	v_add_u32_e32 v66, 0x6400, v130
	ds_write2_b32 v66, v75, v91 offset0:68 offset1:100
	ds_write2_b32 v66, v76, v92 offset0:200 offset1:232
	v_add_u32_e32 v66, 0x6800, v130
	ds_write2_b32 v66, v77, v93 offset0:76 offset1:108
	v_add_u32_e32 v66, 0x7200, v130
	ds_write2_b32 v66, v78, v94 offset0:96 offset1:128
	v_add_u32_e32 v66, 0x7400, v130
	ds_write2_b32 v66, v79, v95 offset0:100 offset1:132
	v_add_u32_e32 v66, 0x7600, v130
	ds_write2_b32 v66, v80, v96 offset0:104 offset1:136
	v_add_u32_e32 v66, 0x7800, v130
	ds_write2_b32 v66, v81, v97 offset0:108 offset1:140
	v_add_u32_e32 v66, 0x8400, v130
	ds_write2_b32 v66, v34, v50 offset1:32
	ds_write2_b32 v66, v35, v51 offset0:132 offset1:164
	v_add_u32_e32 v34, 0x8800, v130
	ds_write2_b32 v34, v36, v52 offset0:8 offset1:40
	ds_write2_b32 v34, v37, v53 offset0:140 offset1:172
	v_add_u32_e32 v34, 0x9400, v130
	ds_write2_b32 v34, v38, v54 offset0:32 offset1:64
	ds_write2_b32 v34, v39, v55 offset0:164 offset1:196
	v_add_u32_e32 v34, 0x9800, v130
	ds_write2_b32 v34, v40, v56 offset0:40 offset1:72
	ds_write2_b32 v34, v41, v57 offset0:172 offset1:204
	v_add_u32_e32 v34, 0xa400, v130
	ds_write2_b32 v34, v42, v58 offset0:64 offset1:96
	ds_write2_b32 v34, v43, v59 offset0:196 offset1:228
	v_add_u32_e32 v34, 0xa800, v130
	ds_write2_b32 v34, v44, v60 offset0:72 offset1:104
	ds_write2_b32 v34, v45, v61 offset0:204 offset1:236
	v_add_u32_e32 v34, 0xb400, v130
	ds_write2_b32 v34, v46, v62 offset0:96 offset1:128
	v_add_u32_e32 v34, 0xb600, v130
	ds_write2_b32 v34, v47, v63 offset0:100 offset1:132
	v_add_u32_e32 v34, 0xb800, v130
	ds_write2_b32 v34, v48, v64 offset0:104 offset1:136
	v_add_u32_e32 v34, 0xba00, v130
	ds_write2_b32 v34, v49, v65 offset0:108 offset1:140
	v_add_u32_e32 v34, 0xc400, v130
	ds_write2_b32 v34, v2, v18 offset0:128 offset1:160
	v_add_u32_e32 v2, 0xc800, v130
	ds_write2_b32 v2, v3, v19 offset0:4 offset1:36
	ds_write2_b32 v2, v4, v20 offset0:136 offset1:168
	v_add_u32_e32 v2, 0xcc00, v130
	ds_write2_b32 v2, v5, v21 offset0:12 offset1:44
	v_add_u32_e32 v2, 0xd400, v130
	ds_write2_b32 v2, v6, v22 offset0:160 offset1:192
	v_add_u32_e32 v2, 0xd800, v130
	ds_write2_b32 v2, v7, v23 offset0:36 offset1:68
	ds_write2_b32 v2, v8, v24 offset0:168 offset1:200
	v_add_u32_e32 v2, 0xdc00, v130
	ds_write2_b32 v2, v9, v25 offset0:44 offset1:76
	v_add_u32_e32 v2, 0xe400, v130
	ds_write2_b32 v2, v10, v26 offset0:192 offset1:224
	v_add_u32_e32 v2, 0xe800, v130
	ds_write2_b32 v2, v11, v27 offset0:68 offset1:100
	ds_write2_b32 v2, v12, v28 offset0:200 offset1:232
	v_add_u32_e32 v2, 0xec00, v130
	ds_write2_b32 v2, v13, v29 offset0:76 offset1:108
	v_add_u32_e32 v2, 0xf600, v130
	ds_write2_b32 v2, v14, v30 offset0:96 offset1:128
	v_add_u32_e32 v2, 0xf800, v130
	ds_write2_b32 v2, v15, v31 offset0:100 offset1:132
	v_add_u32_e32 v2, 0xfa00, v130
	ds_write2_b32 v2, v16, v32 offset0:104 offset1:136
	v_add_u32_e32 v2, 0xfc00, v130
	ds_write2_b32 v2, v17, v33 offset0:108 offset1:140

; DI unsigned pk2(float a, float b) { f32x2 v = {a, b}; bf2_t r = __builtin_convertvector(v, bf2_t); return __builtin_bit_cast(unsigned, r); }
; DI float bf_lo(unsigned u) { return __uint_as_float(u << 16); }
; DI float bf_hi(unsigned u) { return __uint_as_float(u & 0xffff0000u); }
; DI void gemm_up_pass_big(const bf16_t* Y, const bf16_t* W, const bf16_t* __restrict__ GBR, int gcol0, bf16_t* __restrict__ MG, bool first,
;                          int mt, int nt, char* smem) {
;     ...
;     const int r = tid >> 4, ch = tid & 15;
; #pragma unroll 2
;     for (int ps = 0; ps < 8; ++ps) {
;       const int row = ps * 16 + r;
;       const float4 a0 = *(const float4*)(st + row * 132 + ch * 8), a1 = *(const float4*)(st + row * 132 + ch * 8 + 4);
;       const size_t grow = (size_t)(m0 + h * 128 + row);
;       const u32x4 gv = *(const u32x4*)(GBR + grow * 2048 + gcol0 + n0 + ch * 8);
;       float v[8];
;       v[0] = bf_lo(gv.x) * a0.x; v[1] = bf_hi(gv.x) * a0.y; v[2] = bf_lo(gv.y) * a0.z; v[3] = bf_hi(gv.y) * a0.w;
;       v[4] = bf_lo(gv.z) * a1.x; v[5] = bf_hi(gv.z) * a1.y; v[6] = bf_lo(gv.w) * a1.z; v[7] = bf_hi(gv.w) * a1.w;
;       bf16_t* mp = MG + grow * 1024 + n0 + ch * 8;
;       if (!first) {
;         const u32x4 pv = *(const u32x4*)mp;
;         v[0] += bf_lo(pv.x); v[1] += bf_hi(pv.x); v[2] += bf_lo(pv.y); v[3] += bf_hi(pv.y);
;         v[4] += bf_lo(pv.z); v[5] += bf_hi(pv.z); v[6] += bf_lo(pv.w); v[7] += bf_hi(pv.w);
;       }
;       u32x4 ov; ov.x = pk2(v[0], v[1]); ov.y = pk2(v[2], v[3]); ov.z = pk2(v[4], v[5]); ov.w = pk2(v[6], v[7]);
;       *(u32x4*)mp = ov;
;     }
.LBB0_1051:
	v_lshl_add_u64 v[194:195], v[8:9], 0, s[28:29]
	v_lshl_add_u64 v[196:197], v[4:5], 0, s[28:29]
	v_lshl_add_u64 v[202:203], v[6:7], 0, s[28:29]
	v_lshl_add_u64 v[204:205], v[2:3], 0, s[28:29]
	global_load_dwordx4 v[138:141], v[194:195], off
	v_lshl_add_u64 v[194:195], v[194:195], 0, s[92:93]
	global_load_dwordx4 v[142:145], v[196:197], off
	v_lshl_add_u64 v[196:197], v[196:197], 0, s[92:93]
	global_load_dwordx4 v[146:149], v[194:195], off
	v_lshl_add_u64 v[194:195], v[194:195], 0, s[92:93]
	global_load_dwordx4 v[150:153], v[196:197], off
	v_lshl_add_u64 v[196:197], v[196:197], 0, s[92:93]
	ds_read_b128 v[172:175], v0 offset:0
	ds_read_b128 v[176:179], v0 offset:16
	s_waitcnt vmcnt(3) lgkmcnt(0)
	v_lshlrev_b32_e32 v190, 16, v138
	v_and_b32_e32 v191, 0xffff0000, v138
	v_pk_mul_f32 v[172:173], v[172:173], v[190:191]
	v_lshlrev_b32_e32 v190, 16, v139
	v_and_b32_e32 v191, 0xffff0000, v139
	v_pk_mul_f32 v[174:175], v[174:175], v[190:191]
	v_lshlrev_b32_e32 v190, 16, v140
	v_and_b32_e32 v191, 0xffff0000, v140
	v_pk_mul_f32 v[176:177], v[176:177], v[190:191]
	v_lshlrev_b32_e32 v190, 16, v141
	v_and_b32_e32 v191, 0xffff0000, v141
	v_pk_mul_f32 v[178:179], v[178:179], v[190:191]
	v_cvt_pk_bf16_f32 v186, v172, v173
	v_cvt_pk_bf16_f32 v187, v174, v175
	v_cvt_pk_bf16_f32 v188, v176, v177
	v_cvt_pk_bf16_f32 v189, v178, v179
	global_store_dwordx4 v[202:203], v[186:189], off
	s_nop 1
	v_lshl_add_u64 v[202:203], v[202:203], 0, s[38:39]
	global_load_dwordx4 v[138:141], v[194:195], off
	v_lshl_add_u64 v[194:195], v[194:195], 0, s[92:93]
	ds_read_b128 v[172:175], v0 offset:8448
	ds_read_b128 v[176:179], v0 offset:8464
	s_waitcnt vmcnt(4) lgkmcnt(0)
	v_lshlrev_b32_e32 v190, 16, v142
	v_and_b32_e32 v191, 0xffff0000, v142
	v_pk_mul_f32 v[172:173], v[172:173], v[190:191]
	v_lshlrev_b32_e32 v190, 16, v143
	v_and_b32_e32 v191, 0xffff0000, v143
	v_pk_mul_f32 v[174:175], v[174:175], v[190:191]
	v_lshlrev_b32_e32 v190, 16, v144
	v_and_b32_e32 v191, 0xffff0000, v144
	v_pk_mul_f32 v[176:177], v[176:177], v[190:191]
	v_lshlrev_b32_e32 v190, 16, v145
	v_and_b32_e32 v191, 0xffff0000, v145
	v_pk_mul_f32 v[178:179], v[178:179], v[190:191]
	v_cvt_pk_bf16_f32 v186, v172, v173
	v_cvt_pk_bf16_f32 v187, v174, v175
	v_cvt_pk_bf16_f32 v188, v176, v177
	v_cvt_pk_bf16_f32 v189, v178, v179
	global_store_dwordx4 v[204:205], v[186:189], off
	s_nop 1
	v_lshl_add_u64 v[204:205], v[204:205], 0, s[38:39]
	global_load_dwordx4 v[142:145], v[196:197], off
	v_lshl_add_u64 v[196:197], v[196:197], 0, s[92:93]
	ds_read_b128 v[172:175], v0 offset:16896
	ds_read_b128 v[176:179], v0 offset:16912
	s_waitcnt vmcnt(5) lgkmcnt(0)
	v_lshlrev_b32_e32 v190, 16, v146
	v_and_b32_e32 v191, 0xffff0000, v146
	v_pk_mul_f32 v[172:173], v[172:173], v[190:191]
	v_lshlrev_b32_e32 v190, 16, v147
	v_and_b32_e32 v191, 0xffff0000, v147
	v_pk_mul_f32 v[174:175], v[174:175], v[190:191]
	v_lshlrev_b32_e32 v190, 16, v148
	v_and_b32_e32 v191, 0xffff0000, v148
	v_pk_mul_f32 v[176:177], v[176:177], v[190:191]
	v_lshlrev_b32_e32 v190, 16, v149
	v_and_b32_e32 v191, 0xffff0000, v149
	v_pk_mul_f32 v[178:179], v[178:179], v[190:191]
	v_cvt_pk_bf16_f32 v186, v172, v173
	v_cvt_pk_bf16_f32 v187, v174, v175
	v_cvt_pk_bf16_f32 v188, v176, v177
	v_cvt_pk_bf16_f32 v189, v178, v179
	global_store_dwordx4 v[202:203], v[186:189], off
	s_nop 1
	v_lshl_add_u64 v[202:203], v[202:203], 0, s[38:39]
	global_load_dwordx4 v[146:149], v[194:195], off
	v_lshl_add_u64 v[194:195], v[194:195], 0, s[92:93]
	ds_read_b128 v[172:175], v0 offset:25344
	ds_read_b128 v[176:179], v0 offset:25360
	s_waitcnt vmcnt(6) lgkmcnt(0)
	v_lshlrev_b32_e32 v190, 16, v150
	v_and_b32_e32 v191, 0xffff0000, v150
	v_pk_mul_f32 v[172:173], v[172:173], v[190:191]
	v_lshlrev_b32_e32 v190, 16, v151
	v_and_b32_e32 v191, 0xffff0000, v151
	v_pk_mul_f32 v[174:175], v[174:175], v[190:191]
	v_lshlrev_b32_e32 v190, 16, v152
	v_and_b32_e32 v191, 0xffff0000, v152
	v_pk_mul_f32 v[176:177], v[176:177], v[190:191]
	v_lshlrev_b32_e32 v190, 16, v153
	v_and_b32_e32 v191, 0xffff0000, v153
	v_pk_mul_f32 v[178:179], v[178:179], v[190:191]
	v_cvt_pk_bf16_f32 v186, v172, v173
	v_cvt_pk_bf16_f32 v187, v174, v175
	v_cvt_pk_bf16_f32 v188, v176, v177
	v_cvt_pk_bf16_f32 v189, v178, v179
	global_store_dwordx4 v[204:205], v[186:189], off
	s_nop 1
	v_lshl_add_u64 v[204:205], v[204:205], 0, s[38:39]
	global_load_dwordx4 v[150:153], v[196:197], off
	v_lshl_add_u64 v[196:197], v[196:197], 0, s[92:93]
	ds_read_b128 v[172:175], v0 offset:33792
	ds_read_b128 v[176:179], v0 offset:33808
	s_waitcnt vmcnt(6) lgkmcnt(0)
	v_lshlrev_b32_e32 v190, 16, v138
	v_and_b32_e32 v191, 0xffff0000, v138
	v_pk_mul_f32 v[172:173], v[172:173], v[190:191]
	v_lshlrev_b32_e32 v190, 16, v139
	v_and_b32_e32 v191, 0xffff0000, v139
	v_pk_mul_f32 v[174:175], v[174:175], v[190:191]
	v_lshlrev_b32_e32 v190, 16, v140
	v_and_b32_e32 v191, 0xffff0000, v140
	v_pk_mul_f32 v[176:177], v[176:177], v[190:191]
	v_lshlrev_b32_e32 v190, 16, v141
	v_and_b32_e32 v191, 0xffff0000, v141
	v_pk_mul_f32 v[178:179], v[178:179], v[190:191]
	v_cvt_pk_bf16_f32 v186, v172, v173
	v_cvt_pk_bf16_f32 v187, v174, v175
	v_cvt_pk_bf16_f32 v188, v176, v177
	v_cvt_pk_bf16_f32 v189, v178, v179
	global_store_dwordx4 v[202:203], v[186:189], off
	s_nop 1
	v_lshl_add_u64 v[202:203], v[202:203], 0, s[38:39]
	ds_read_b128 v[172:175], v0 offset:42240
	ds_read_b128 v[176:179], v0 offset:42256
	s_waitcnt vmcnt(5) lgkmcnt(0)
; DI void gemm_mainloop_big(const bf16_t* __restrict__ A, int lda, const bf16_t* __restrict__ Bt, int ldb, int K, int m0, int n0,
;                           f32x16 (&acc)[4][2], char* smem) {
;   bf16_t (*sa)[72] = (bf16_t (*)[72])smem;
;   bf16_t (*sb)[72] = (bf16_t (*)[72])(smem + 256 * 72 * 2);
;   const int tid = otid(), lane = tid & 63, w = tid >> 6, wm = w >> 1, wn = w & 1;
;   const int r = lane & 31, half = lane >> 5;
;   const int nk = K >> 6;
;   u32x4 ra[8], rb[4];
;   const bf16_t* ap = A + (size_t)(m0 + (tid >> 3)) * lda + (tid & 7) * 8;
;   const bf16_t* bp = Bt + (size_t)(n0 + (tid >> 3)) * ldb + (tid & 7) * 8;
; #pragma unroll
;   for (int i = 0; i < 8; ++i) ra[i] = *(const u32x4*)(ap + (size_t)(32 * i) * lda);
; #pragma unroll
;   for (int i = 0; i < 4; ++i) rb[i] = *(const u32x4*)(bp + (size_t)(32 * i) * ldb);
;   __syncthreads();
; #pragma unroll
;   for (int i = 0; i < 8; ++i) *(u32x4*)&sa[(tid >> 3) + 32 * i][(tid & 7) * 8] = ra[i];
; #pragma unroll
;   for (int i = 0; i < 4; ++i) *(u32x4*)&sb[(tid >> 3) + 32 * i][(tid & 7) * 8] = rb[i];
;   __syncthreads();
; DI void gemm_up_pass_big(const bf16_t* Y, const bf16_t* W, const bf16_t* __restrict__ GBR, int gcol0, bf16_t* __restrict__ MG, bool first,
;                          int mt, int nt, char* smem) {
;     ...
;     for (int ps = 0; ps < 8; ++ps) {
;       const int row = ps * 16 + r;
;       const float4 a0 = *(const float4*)(st + row * 132 + ch * 8), a1 = *(const float4*)(st + row * 132 + ch * 8 + 4);
;       const size_t grow = (size_t)(m0 + h * 128 + row);
;       const u32x4 gv = *(const u32x4*)(GBR + grow * 2048 + gcol0 + n0 + ch * 8);
;       float v[8];
;       v[0] = bf_lo(gv.x) * a0.x; v[1] = bf_hi(gv.x) * a0.y; v[2] = bf_lo(gv.y) * a0.z; v[3] = bf_hi(gv.y) * a0.w;
;       v[4] = bf_lo(gv.z) * a1.x; v[5] = bf_hi(gv.z) * a1.y; v[6] = bf_lo(gv.w) * a1.z; v[7] = bf_hi(gv.w) * a1.w;
;       bf16_t* mp = MG + grow * 1024 + n0 + ch * 8;
;       if (!first) {
;         const u32x4 pv = *(const u32x4*)mp;
;         v[0] += bf_lo(pv.x); v[1] += bf_hi(pv.x); v[2] += bf_lo(pv.y); v[3] += bf_hi(pv.y);
;         v[4] += bf_lo(pv.z); v[5] += bf_hi(pv.z); v[6] += bf_lo(pv.w); v[7] += bf_hi(pv.w);
;       }
;       u32x4 ov; ov.x = pk2(v[0], v[1]); ov.y = pk2(v[2], v[3]); ov.z = pk2(v[4], v[5]); ov.w = pk2(v[6], v[7]);
;       *(u32x4*)mp = ov;
;     }
;     __syncthreads();
	v_lshlrev_b32_e32 v190, 16, v142
	v_and_b32_e32 v191, 0xffff0000, v142
	v_pk_mul_f32 v[172:173], v[172:173], v[190:191]
	v_lshlrev_b32_e32 v190, 16, v143
	v_and_b32_e32 v191, 0xffff0000, v143
	v_pk_mul_f32 v[174:175], v[174:175], v[190:191]
	v_lshlrev_b32_e32 v190, 16, v144
	v_and_b32_e32 v191, 0xffff0000, v144
	v_pk_mul_f32 v[176:177], v[176:177], v[190:191]
	v_lshlrev_b32_e32 v190, 16, v145
	v_and_b32_e32 v191, 0xffff0000, v145
	v_pk_mul_f32 v[178:179], v[178:179], v[190:191]
	v_cvt_pk_bf16_f32 v186, v172, v173
	v_cvt_pk_bf16_f32 v187, v174, v175
	v_cvt_pk_bf16_f32 v188, v176, v177
	v_cvt_pk_bf16_f32 v189, v178, v179
	global_store_dwordx4 v[204:205], v[186:189], off
	s_nop 1
	v_lshl_add_u64 v[204:205], v[204:205], 0, s[38:39]
	ds_read_b128 v[172:175], v0 offset:50688
	ds_read_b128 v[176:179], v0 offset:50704
	s_waitcnt vmcnt(4) lgkmcnt(0)
	v_lshlrev_b32_e32 v190, 16, v146
	v_and_b32_e32 v191, 0xffff0000, v146
	v_pk_mul_f32 v[172:173], v[172:173], v[190:191]
	v_lshlrev_b32_e32 v190, 16, v147
	v_and_b32_e32 v191, 0xffff0000, v147
	v_pk_mul_f32 v[174:175], v[174:175], v[190:191]
	v_lshlrev_b32_e32 v190, 16, v148
	v_and_b32_e32 v191, 0xffff0000, v148
	v_pk_mul_f32 v[176:177], v[176:177], v[190:191]
	v_lshlrev_b32_e32 v190, 16, v149
	v_and_b32_e32 v191, 0xffff0000, v149
	v_pk_mul_f32 v[178:179], v[178:179], v[190:191]
	v_cvt_pk_bf16_f32 v186, v172, v173
	v_cvt_pk_bf16_f32 v187, v174, v175
	v_cvt_pk_bf16_f32 v188, v176, v177
	v_cvt_pk_bf16_f32 v189, v178, v179
	global_store_dwordx4 v[202:203], v[186:189], off
	s_nop 1
	v_lshl_add_u64 v[202:203], v[202:203], 0, s[38:39]
	ds_read_b128 v[172:175], v0 offset:59136
	ds_read_b128 v[176:179], v0 offset:59152
	s_waitcnt vmcnt(3) lgkmcnt(0)
	v_lshlrev_b32_e32 v190, 16, v150
	v_and_b32_e32 v191, 0xffff0000, v150
	v_pk_mul_f32 v[172:173], v[172:173], v[190:191]
	v_lshlrev_b32_e32 v190, 16, v151
	v_and_b32_e32 v191, 0xffff0000, v151
	v_pk_mul_f32 v[174:175], v[174:175], v[190:191]
	v_lshlrev_b32_e32 v190, 16, v152
	v_and_b32_e32 v191, 0xffff0000, v152
	v_pk_mul_f32 v[176:177], v[176:177], v[190:191]
	v_lshlrev_b32_e32 v190, 16, v153
	v_and_b32_e32 v191, 0xffff0000, v153
	v_pk_mul_f32 v[178:179], v[178:179], v[190:191]
	v_cvt_pk_bf16_f32 v186, v172, v173
	v_cvt_pk_bf16_f32 v187, v174, v175
	v_cvt_pk_bf16_f32 v188, v176, v177
	v_cvt_pk_bf16_f32 v189, v178, v179
	global_store_dwordx4 v[204:205], v[186:189], off
	s_nop 1
	v_lshl_add_u64 v[204:205], v[204:205], 0, s[38:39]
	v_mov_b32_e32 v50, v216
	s_barrier
	v_readlane_b32 s42, v244, 40
	v_ashrrev_i32_e32 v51, 3, v50
	v_add_u32_e32 v2, s47, v51
	v_ashrrev_i32_e32 v3, 31, v2
	v_lshlrev_b64 v[2:3], 10, v[2:3]
	v_readlane_b32 s43, v244, 41
	v_lshlrev_b32_e32 v0, 4, v50
	v_and_b32_e32 v0, 0x70, v0
	v_lshl_add_u64 v[2:3], s[42:43], 0, v[2:3]
	v_lshl_add_u64 v[130:131], v[2:3], 0, v[0:1]
	s_mov_b32 s43, 0x8000
	v_add_co_u32_e32 v132, vcc, s43, v130
	s_mov_b32 s42, 0x18000
	s_nop 0
	v_addc_co_u32_e32 v133, vcc, 0, v131, vcc
	v_add_co_u32_e32 v134, vcc, s34, v130
	v_add_u32_e32 v2, s46, v51
	s_nop 0
	v_addc_co_u32_e32 v135, vcc, 0, v131, vcc
	v_add_co_u32_e32 v136, vcc, s42, v130
	s_mov_b32 s46, 0x28000
	s_nop 0
	v_addc_co_u32_e32 v137, vcc, 0, v131, vcc
	v_add_co_u32_e32 v138, vcc, s35, v130
	v_ashrrev_i32_e32 v3, 31, v2
	s_nop 0
	v_addc_co_u32_e32 v139, vcc, 0, v131, vcc
	v_add_co_u32_e32 v140, vcc, s46, v130
	v_lshlrev_b64 v[2:3], 10, v[2:3]
	s_nop 0
	v_addc_co_u32_e32 v141, vcc, 0, v131, vcc
	v_add_co_u32_e32 v142, vcc, s17, v130
	s_mov_b32 s46, 0x38000
	s_nop 0
	v_addc_co_u32_e32 v143, vcc, 0, v131, vcc
	v_lshl_add_u64 v[34:35], s[26:27], 0, v[2:3]
	v_add_co_u32_e32 v144, vcc, s46, v130
	v_lshl_add_u64 v[146:147], v[34:35], 0, v[0:1]
	s_nop 0
	v_addc_co_u32_e32 v145, vcc, 0, v131, vcc
	v_add_co_u32_e32 v150, vcc, s43, v146
	global_load_dwordx4 v[2:5], v[130:131], off
	global_load_dwordx4 v[6:9], v[132:133], off
	v_addc_co_u32_e32 v151, vcc, 0, v147, vcc
	v_add_co_u32_e32 v152, vcc, s34, v146
	global_load_dwordx4 v[10:13], v[134:135], off
	global_load_dwordx4 v[14:17], v[136:137], off
	v_addc_co_u32_e32 v153, vcc, 0, v147, vcc
	v_add_co_u32_e32 v154, vcc, s42, v146
	global_load_dwordx4 v[18:21], v[138:139], off
	global_load_dwordx4 v[22:25], v[140:141], off
	global_load_dwordx4 v[26:29], v[142:143], off
	global_load_dwordx4 v[30:33], v[144:145], off
	global_load_dwordx4 v[34:37], v[146:147], off
	global_load_dwordx4 v[38:41], v[150:151], off
	v_addc_co_u32_e32 v155, vcc, 0, v147, vcc
	global_load_dwordx4 v[42:45], v[152:153], off
	global_load_dwordx4 v[46:49], v[154:155], off
	s_movk_i32 s46, 0x90
	v_mad_u64_u32 v[148:149], s[42:43], v51, s46, v[0:1]
	v_and_b32_e32 v0, 31, v50
	s_barrier
	s_waitcnt vmcnt(11)
	ds_write_b128 v148, v[2:5]
	s_waitcnt vmcnt(3)
	ds_write_b128 v148, v[34:37] offset:36864
	ds_write_b128 v148, v[6:9] offset:4608
	ds_write_b128 v148, v[10:13] offset:9216
	ds_write_b128 v148, v[14:17] offset:13824
	ds_write_b128 v148, v[18:21] offset:18432
	ds_write_b128 v148, v[22:25] offset:23040
	ds_write_b128 v148, v[26:29] offset:27648
	ds_write_b128 v148, v[30:33] offset:32256
	s_waitcnt vmcnt(2)
	ds_write_b128 v148, v[38:41] offset:41472
	s_waitcnt vmcnt(1)
	ds_write_b128 v148, v[42:45] offset:46080
	s_waitcnt vmcnt(0)
	ds_write_b128 v148, v[46:49] offset:50688
	v_mul_u32_u24_e32 v6, 0x90, v0
	v_and_b32_e32 v0, 0xfffff80, v50
	v_lshrrev_b32_e32 v2, 1, v50
	v_mul_lo_u32 v0, v0, s46
	v_and_b32_e32 v7, 16, v2
	v_add3_u32 v0, v6, v0, v7
	s_waitcnt lgkmcnt(0)
	s_barrier
; #define MFMA32(a, b, c) __builtin_amdgcn_mfma_f32_32x32x16_bf16((a), (b), (c), 0, 0, 0)
; DI void gemm_mainloop_big(const bf16_t* __restrict__ A, int lda, const bf16_t* __restrict__ Bt, int ldb, int K, int m0, int n0,
;                           f32x16 (&acc)[4][2], char* smem) {
;     ...
;   for (int kt = 0; kt < nk; ++kt) {
;     if (kt + 1 < nk) {
; #pragma unroll
;       for (int i = 0; i < 8; ++i) ra[i] = *(const u32x4*)(ap + (size_t)(32 * i) * lda + (kt + 1) * 64);
; #pragma unroll
;       for (int i = 0; i < 4; ++i) rb[i] = *(const u32x4*)(bp + (size_t)(32 * i) * ldb + (kt + 1) * 64);
;     }
; #pragma unroll
;     for (int ks = 0; ks < 4; ++ks) {
;       bf16x8 af[4], bfr[2];
; #pragma unroll
;       for (int f = 0; f < 4; ++f) af[f] = *(const bf16x8*)&sa[wm * 128 + f * 32 + r][ks * 16 + half * 8];
; #pragma unroll
;       for (int f = 0; f < 2; ++f) bfr[f] = *(const bf16x8*)&sb[wn * 64 + f * 32 + r][ks * 16 + half * 8];
; #pragma unroll
;       for (int mf = 0; mf < 4; ++mf)
; #pragma unroll
;         for (int nf = 0; nf < 2; ++nf) acc[mf][nf] = MFMA32(af[mf], bfr[nf], acc[mf][nf]);
;     }
;     __syncthreads();
;     if (kt + 1 < nk) {
; #pragma unroll
;       for (int i = 0; i < 8; ++i) *(u32x4*)&sa[(tid >> 3) + 32 * i][(tid & 7) * 8] = ra[i];
; #pragma unroll
;       for (int i = 0; i < 4; ++i) *(u32x4*)&sb[(tid >> 3) + 32 * i][(tid & 7) * 8] = rb[i];
;     }
;     __syncthreads();
	ds_read_b128 v[2:5], v0
	v_and_b32_e32 v8, 64, v50
	v_mul_u32_u24_e32 v8, 0x90, v8
	v_add3_u32 v149, v6, v8, v7
	ds_read_b128 v[6:9], v149 offset:36864
	ds_read_b128 v[156:159], v0 offset:32
	ds_read_b128 v[160:163], v149 offset:36896
	ds_read_b128 v[18:21], v149 offset:41472
	ds_read_b128 v[164:167], v149 offset:41504
	s_waitcnt lgkmcnt(4)
	v_mfma_f32_32x32x16_bf16 v[98:113], v[2:5], v[6:9], 0
	s_waitcnt lgkmcnt(1)
	v_mfma_f32_32x32x16_bf16 v[114:129], v[2:5], v[18:21], 0
	ds_read_b128 v[2:5], v0 offset:4608
	ds_read_b128 v[168:171], v0 offset:4640
	s_waitcnt lgkmcnt(1)
	v_mfma_f32_32x32x16_bf16 v[66:81], v[2:5], v[6:9], 0
	v_mfma_f32_32x32x16_bf16 v[82:97], v[2:5], v[18:21], 0
	ds_read_b128 v[2:5], v0 offset:9216
	ds_read_b128 v[172:175], v0 offset:9248
	ds_read_b128 v[22:25], v0 offset:13824
	ds_read_b128 v[176:179], v0 offset:13856
	s_waitcnt lgkmcnt(3)
	v_mfma_f32_32x32x16_bf16 v[34:49], v[2:5], v[6:9], 0
	v_mfma_f32_32x32x16_bf16 v[50:65], v[2:5], v[18:21], 0
	s_waitcnt lgkmcnt(1)
	v_mfma_f32_32x32x16_bf16 v[2:17], v[22:25], v[6:9], 0
	v_mfma_f32_32x32x16_bf16 v[18:33], v[22:25], v[18:21], 0
	v_mfma_f32_32x32x16_bf16 v[98:113], v[156:159], v[160:163], v[98:113]
	v_mfma_f32_32x32x16_bf16 v[114:129], v[156:159], v[164:167], v[114:129]
	v_mfma_f32_32x32x16_bf16 v[66:81], v[168:171], v[160:163], v[66:81]
	v_mfma_f32_32x32x16_bf16 v[82:97], v[168:171], v[164:167], v[82:97]
	v_mfma_f32_32x32x16_bf16 v[34:49], v[172:175], v[160:163], v[34:49]
	v_mfma_f32_32x32x16_bf16 v[50:65], v[172:175], v[164:167], v[50:65]
	s_waitcnt lgkmcnt(0)
	v_mfma_f32_32x32x16_bf16 v[2:17], v[176:179], v[160:163], v[2:17]
	v_mfma_f32_32x32x16_bf16 v[18:33], v[176:179], v[164:167], v[18:33]
	ds_read_b128 v[156:159], v0 offset:64
	ds_read_b128 v[160:163], v149 offset:36928
	ds_read_b128 v[164:167], v0 offset:96
	ds_read_b128 v[168:171], v149 offset:36960
	ds_read_b128 v[172:175], v149 offset:41536
	ds_read_b128 v[176:179], v149 offset:41568
	s_waitcnt lgkmcnt(4)
	v_mfma_f32_32x32x16_bf16 v[98:113], v[156:159], v[160:163], v[98:113]
	s_waitcnt lgkmcnt(1)
	v_mfma_f32_32x32x16_bf16 v[114:129], v[156:159], v[172:175], v[114:129]
	ds_read_b128 v[156:159], v0 offset:4672
	ds_read_b128 v[186:189], v0 offset:4704
	s_waitcnt lgkmcnt(1)
	v_mfma_f32_32x32x16_bf16 v[66:81], v[156:159], v[160:163], v[66:81]
	v_mfma_f32_32x32x16_bf16 v[82:97], v[156:159], v[172:175], v[82:97]
	ds_read_b128 v[156:159], v0 offset:9280
	ds_read_b128 v[190:193], v0 offset:9312
	s_waitcnt lgkmcnt(1)
	v_mfma_f32_32x32x16_bf16 v[34:49], v[156:159], v[160:163], v[34:49]
	v_mfma_f32_32x32x16_bf16 v[50:65], v[156:159], v[172:175], v[50:65]
	ds_read_b128 v[156:159], v0 offset:13888
	ds_read_b128 v[194:197], v0 offset:13920
	s_waitcnt lgkmcnt(1)
	v_mfma_f32_32x32x16_bf16 v[2:17], v[156:159], v[160:163], v[2:17]
	v_mfma_f32_32x32x16_bf16 v[18:33], v[156:159], v[172:175], v[18:33]
	global_load_dwordx4 v[156:159], v[130:131], off offset:128
	global_load_dwordx4 v[160:163], v[132:133], off offset:128
	v_mfma_f32_32x32x16_bf16 v[98:113], v[164:167], v[168:171], v[98:113]
	v_mfma_f32_32x32x16_bf16 v[114:129], v[164:167], v[176:179], v[114:129]
	v_mfma_f32_32x32x16_bf16 v[66:81], v[186:189], v[168:171], v[66:81]
	v_mfma_f32_32x32x16_bf16 v[82:97], v[186:189], v[176:179], v[82:97]
	v_mfma_f32_32x32x16_bf16 v[34:49], v[190:193], v[168:171], v[34:49]
	v_mfma_f32_32x32x16_bf16 v[50:65], v[190:193], v[176:179], v[50:65]
	global_load_dwordx4 v[164:167], v[134:135], off offset:128
	global_load_dwordx4 v[172:175], v[136:137], off offset:128
	global_load_dwordx4 v[186:189], v[138:139], off offset:128
	global_load_dwordx4 v[190:193], v[140:141], off offset:128
	global_load_dwordx4 v[198:201], v[142:143], off offset:128
	global_load_dwordx4 v[202:205], v[144:145], off offset:128
	global_load_dwordx4 v[206:209], v[146:147], off offset:128
	global_load_dwordx4 v[210:213], v[150:151], off offset:128
	s_waitcnt lgkmcnt(0)
	v_mfma_f32_32x32x16_bf16 v[2:17], v[194:197], v[168:171], v[2:17]
	global_load_dwordx4 v[168:171], v[152:153], off offset:128
	global_load_dwordx4 v[236:239], v[154:155], off offset:128
	s_barrier
	s_waitcnt vmcnt(11)
	ds_write_b128 v148, v[156:159]
	s_waitcnt vmcnt(10)
	ds_write_b128 v148, v[160:163] offset:4608
	s_waitcnt vmcnt(9)
	ds_write_b128 v148, v[164:167] offset:9216
	s_waitcnt vmcnt(8)
	ds_write_b128 v148, v[172:175] offset:13824
	s_waitcnt vmcnt(7)
	ds_write_b128 v148, v[186:189] offset:18432
	s_waitcnt vmcnt(6)
	ds_write_b128 v148, v[190:193] offset:23040
	s_waitcnt vmcnt(5)
	ds_write_b128 v148, v[198:201] offset:27648
	s_waitcnt vmcnt(4)
	ds_write_b128 v148, v[202:205] offset:32256
	s_waitcnt vmcnt(3)
	ds_write_b128 v148, v[206:209] offset:36864
	s_waitcnt vmcnt(2)
	ds_write_b128 v148, v[210:213] offset:41472
	s_waitcnt vmcnt(1)
	ds_write_b128 v148, v[168:171] offset:46080
	s_waitcnt vmcnt(0)
	ds_write_b128 v148, v[236:239] offset:50688
	v_mfma_f32_32x32x16_bf16 v[18:33], v[194:197], v[176:179], v[18:33]
	s_waitcnt lgkmcnt(0)
	s_barrier
; #define MFMA32(a, b, c) __builtin_amdgcn_mfma_f32_32x32x16_bf16((a), (b), (c), 0, 0, 0)
; DI void gemm_mainloop_big(const bf16_t* __restrict__ A, int lda, const bf16_t* __restrict__ Bt, int ldb, int K, int m0, int n0,
;                           f32x16 (&acc)[4][2], char* smem) {
;     ...
;   for (int kt = 0; kt < nk; ++kt) {
;     if (kt + 1 < nk) {
; #pragma unroll
;       for (int i = 0; i < 8; ++i) ra[i] = *(const u32x4*)(ap + (size_t)(32 * i) * lda + (kt + 1) * 64);
; #pragma unroll
;       for (int i = 0; i < 4; ++i) rb[i] = *(const u32x4*)(bp + (size_t)(32 * i) * ldb + (kt + 1) * 64);
;     }
; #pragma unroll
;     for (int ks = 0; ks < 4; ++ks) {
;       bf16x8 af[4], bfr[2];
; #pragma unroll
;       for (int f = 0; f < 4; ++f) af[f] = *(const bf16x8*)&sa[wm * 128 + f * 32 + r][ks * 16 + half * 8];
; #pragma unroll
;       for (int f = 0; f < 2; ++f) bfr[f] = *(const bf16x8*)&sb[wn * 64 + f * 32 + r][ks * 16 + half * 8];
; #pragma unroll
;       for (int mf = 0; mf < 4; ++mf)
; #pragma unroll
;         for (int nf = 0; nf < 2; ++nf) acc[mf][nf] = MFMA32(af[mf], bfr[nf], acc[mf][nf]);
;     }
;     __syncthreads();
;     if (kt + 1 < nk) {
; #pragma unroll
;       for (int i = 0; i < 8; ++i) *(u32x4*)&sa[(tid >> 3) + 32 * i][(tid & 7) * 8] = ra[i];
; #pragma unroll
;       for (int i = 0; i < 4; ++i) *(u32x4*)&sb[(tid >> 3) + 32 * i][(tid & 7) * 8] = rb[i];
;     }
;     __syncthreads();
	ds_read_b128 v[156:159], v0
	ds_read_b128 v[160:163], v149 offset:36864
	ds_read_b128 v[164:167], v0 offset:32
	ds_read_b128 v[168:171], v149 offset:36896
	ds_read_b128 v[172:175], v149 offset:41472
	ds_read_b128 v[176:179], v149 offset:41504
	s_waitcnt lgkmcnt(4)
	v_mfma_f32_32x32x16_bf16 v[98:113], v[156:159], v[160:163], v[98:113]
	s_waitcnt lgkmcnt(1)
	v_mfma_f32_32x32x16_bf16 v[114:129], v[156:159], v[172:175], v[114:129]
	ds_read_b128 v[156:159], v0 offset:4608
	ds_read_b128 v[186:189], v0 offset:4640
	s_waitcnt lgkmcnt(1)
	v_mfma_f32_32x32x16_bf16 v[66:81], v[156:159], v[160:163], v[66:81]
	v_mfma_f32_32x32x16_bf16 v[82:97], v[156:159], v[172:175], v[82:97]
	ds_read_b128 v[156:159], v0 offset:9216
	ds_read_b128 v[190:193], v0 offset:9248
	s_waitcnt lgkmcnt(1)
	v_mfma_f32_32x32x16_bf16 v[34:49], v[156:159], v[160:163], v[34:49]
	v_mfma_f32_32x32x16_bf16 v[50:65], v[156:159], v[172:175], v[50:65]
	ds_read_b128 v[156:159], v0 offset:13824
	ds_read_b128 v[194:197], v0 offset:13856
	s_waitcnt lgkmcnt(1)
	v_mfma_f32_32x32x16_bf16 v[2:17], v[156:159], v[160:163], v[2:17]
	v_mfma_f32_32x32x16_bf16 v[18:33], v[156:159], v[172:175], v[18:33]
	v_mfma_f32_32x32x16_bf16 v[98:113], v[164:167], v[168:171], v[98:113]
	v_mfma_f32_32x32x16_bf16 v[114:129], v[164:167], v[176:179], v[114:129]
	v_mfma_f32_32x32x16_bf16 v[66:81], v[186:189], v[168:171], v[66:81]
	v_mfma_f32_32x32x16_bf16 v[82:97], v[186:189], v[176:179], v[82:97]
	v_mfma_f32_32x32x16_bf16 v[34:49], v[190:193], v[168:171], v[34:49]
	v_mfma_f32_32x32x16_bf16 v[50:65], v[190:193], v[176:179], v[50:65]
	s_waitcnt lgkmcnt(0)
	v_mfma_f32_32x32x16_bf16 v[2:17], v[194:197], v[168:171], v[2:17]
	ds_read_b128 v[156:159], v0 offset:64
	ds_read_b128 v[160:163], v149 offset:36928
	ds_read_b128 v[164:167], v0 offset:96
	ds_read_b128 v[168:171], v149 offset:36960
	v_mfma_f32_32x32x16_bf16 v[18:33], v[194:197], v[176:179], v[18:33]
	ds_read_b128 v[172:175], v149 offset:41536
	ds_read_b128 v[176:179], v149 offset:41568
	s_waitcnt lgkmcnt(4)
	v_mfma_f32_32x32x16_bf16 v[98:113], v[156:159], v[160:163], v[98:113]
	s_waitcnt lgkmcnt(1)
	v_mfma_f32_32x32x16_bf16 v[114:129], v[156:159], v[172:175], v[114:129]
	ds_read_b128 v[156:159], v0 offset:4672
	ds_read_b128 v[186:189], v0 offset:4704
	s_waitcnt lgkmcnt(1)
	v_mfma_f32_32x32x16_bf16 v[66:81], v[156:159], v[160:163], v[66:81]
	v_mfma_f32_32x32x16_bf16 v[82:97], v[156:159], v[172:175], v[82:97]
	ds_read_b128 v[156:159], v0 offset:9280
	ds_read_b128 v[190:193], v0 offset:9312
	s_waitcnt lgkmcnt(1)
	v_mfma_f32_32x32x16_bf16 v[34:49], v[156:159], v[160:163], v[34:49]
	v_mfma_f32_32x32x16_bf16 v[50:65], v[156:159], v[172:175], v[50:65]
	ds_read_b128 v[156:159], v0 offset:13888
	ds_read_b128 v[194:197], v0 offset:13920
	s_waitcnt lgkmcnt(1)
	v_mfma_f32_32x32x16_bf16 v[2:17], v[156:159], v[160:163], v[2:17]
	v_mfma_f32_32x32x16_bf16 v[18:33], v[156:159], v[172:175], v[18:33]
	global_load_dwordx4 v[156:159], v[130:131], off offset:256
	global_load_dwordx4 v[160:163], v[132:133], off offset:256
	v_mfma_f32_32x32x16_bf16 v[98:113], v[164:167], v[168:171], v[98:113]
	v_mfma_f32_32x32x16_bf16 v[114:129], v[164:167], v[176:179], v[114:129]
	v_mfma_f32_32x32x16_bf16 v[66:81], v[186:189], v[168:171], v[66:81]
	v_mfma_f32_32x32x16_bf16 v[82:97], v[186:189], v[176:179], v[82:97]
	v_mfma_f32_32x32x16_bf16 v[34:49], v[190:193], v[168:171], v[34:49]
	v_mfma_f32_32x32x16_bf16 v[50:65], v[190:193], v[176:179], v[50:65]
	global_load_dwordx4 v[164:167], v[134:135], off offset:256
	global_load_dwordx4 v[172:175], v[136:137], off offset:256
	global_load_dwordx4 v[186:189], v[138:139], off offset:256
	global_load_dwordx4 v[190:193], v[140:141], off offset:256
	global_load_dwordx4 v[198:201], v[142:143], off offset:256
	global_load_dwordx4 v[202:205], v[144:145], off offset:256
	global_load_dwordx4 v[206:209], v[146:147], off offset:256
	global_load_dwordx4 v[210:213], v[150:151], off offset:256
	s_waitcnt lgkmcnt(0)
	v_mfma_f32_32x32x16_bf16 v[2:17], v[194:197], v[168:171], v[2:17]
	global_load_dwordx4 v[168:171], v[152:153], off offset:256
	global_load_dwordx4 v[236:239], v[154:155], off offset:256
	s_barrier
	s_waitcnt vmcnt(11)
	ds_write_b128 v148, v[156:159]
	s_waitcnt vmcnt(10)
	ds_write_b128 v148, v[160:163] offset:4608
	s_waitcnt vmcnt(9)
	ds_write_b128 v148, v[164:167] offset:9216
	s_waitcnt vmcnt(8)
	ds_write_b128 v148, v[172:175] offset:13824
	s_waitcnt vmcnt(7)
	ds_write_b128 v148, v[186:189] offset:18432
	s_waitcnt vmcnt(6)
	ds_write_b128 v148, v[190:193] offset:23040
	s_waitcnt vmcnt(5)
	ds_write_b128 v148, v[198:201] offset:27648
	s_waitcnt vmcnt(4)
	ds_write_b128 v148, v[202:205] offset:32256
	s_waitcnt vmcnt(3)
	ds_write_b128 v148, v[206:209] offset:36864
	s_waitcnt vmcnt(2)
	ds_write_b128 v148, v[210:213] offset:41472
	s_waitcnt vmcnt(1)
	ds_write_b128 v148, v[168:171] offset:46080
	s_waitcnt vmcnt(0)
	ds_write_b128 v148, v[236:239] offset:50688
	v_mfma_f32_32x32x16_bf16 v[18:33], v[194:197], v[176:179], v[18:33]
	s_waitcnt lgkmcnt(0)
	s_barrier
; #define MFMA32(a, b, c) __builtin_amdgcn_mfma_f32_32x32x16_bf16((a), (b), (c), 0, 0, 0)
; DI void gemm_mainloop_big(const bf16_t* __restrict__ A, int lda, const bf16_t* __restrict__ Bt, int ldb, int K, int m0, int n0,
;                           f32x16 (&acc)[4][2], char* smem) {
;     ...
;   for (int kt = 0; kt < nk; ++kt) {
;     if (kt + 1 < nk) {
; #pragma unroll
;       for (int i = 0; i < 8; ++i) ra[i] = *(const u32x4*)(ap + (size_t)(32 * i) * lda + (kt + 1) * 64);
; #pragma unroll
;       for (int i = 0; i < 4; ++i) rb[i] = *(const u32x4*)(bp + (size_t)(32 * i) * ldb + (kt + 1) * 64);
;     }
; #pragma unroll
;     for (int ks = 0; ks < 4; ++ks) {
;       bf16x8 af[4], bfr[2];
; #pragma unroll
;       for (int f = 0; f < 4; ++f) af[f] = *(const bf16x8*)&sa[wm * 128 + f * 32 + r][ks * 16 + half * 8];
; #pragma unroll
;       for (int f = 0; f < 2; ++f) bfr[f] = *(const bf16x8*)&sb[wn * 64 + f * 32 + r][ks * 16 + half * 8];
; #pragma unroll
;       for (int mf = 0; mf < 4; ++mf)
; #pragma unroll
;         for (int nf = 0; nf < 2; ++nf) acc[mf][nf] = MFMA32(af[mf], bfr[nf], acc[mf][nf]);
;     }
;     __syncthreads();
;     if (kt + 1 < nk) {
; #pragma unroll
;       for (int i = 0; i < 8; ++i) *(u32x4*)&sa[(tid >> 3) + 32 * i][(tid & 7) * 8] = ra[i];
; #pragma unroll
;       for (int i = 0; i < 4; ++i) *(u32x4*)&sb[(tid >> 3) + 32 * i][(tid & 7) * 8] = rb[i];
;     }
;     __syncthreads();
	ds_read_b128 v[156:159], v0
	ds_read_b128 v[160:163], v149 offset:36864
	ds_read_b128 v[164:167], v0 offset:32
	ds_read_b128 v[168:171], v149 offset:36896
	ds_read_b128 v[172:175], v149 offset:41472
	ds_read_b128 v[176:179], v149 offset:41504
	s_waitcnt lgkmcnt(4)
	v_mfma_f32_32x32x16_bf16 v[98:113], v[156:159], v[160:163], v[98:113]
	s_waitcnt lgkmcnt(1)
	v_mfma_f32_32x32x16_bf16 v[114:129], v[156:159], v[172:175], v[114:129]
	ds_read_b128 v[156:159], v0 offset:4608
	ds_read_b128 v[186:189], v0 offset:4640
	s_waitcnt lgkmcnt(1)
	v_mfma_f32_32x32x16_bf16 v[66:81], v[156:159], v[160:163], v[66:81]
	v_mfma_f32_32x32x16_bf16 v[82:97], v[156:159], v[172:175], v[82:97]
	ds_read_b128 v[156:159], v0 offset:9216
	ds_read_b128 v[190:193], v0 offset:9248
	s_waitcnt lgkmcnt(1)
	v_mfma_f32_32x32x16_bf16 v[34:49], v[156:159], v[160:163], v[34:49]
	v_mfma_f32_32x32x16_bf16 v[50:65], v[156:159], v[172:175], v[50:65]
	ds_read_b128 v[156:159], v0 offset:13824
	ds_read_b128 v[194:197], v0 offset:13856
	s_waitcnt lgkmcnt(1)
	v_mfma_f32_32x32x16_bf16 v[2:17], v[156:159], v[160:163], v[2:17]
	v_mfma_f32_32x32x16_bf16 v[18:33], v[156:159], v[172:175], v[18:33]
	v_mfma_f32_32x32x16_bf16 v[98:113], v[164:167], v[168:171], v[98:113]
	v_mfma_f32_32x32x16_bf16 v[114:129], v[164:167], v[176:179], v[114:129]
	v_mfma_f32_32x32x16_bf16 v[66:81], v[186:189], v[168:171], v[66:81]
	v_mfma_f32_32x32x16_bf16 v[82:97], v[186:189], v[176:179], v[82:97]
	v_mfma_f32_32x32x16_bf16 v[34:49], v[190:193], v[168:171], v[34:49]
	v_mfma_f32_32x32x16_bf16 v[50:65], v[190:193], v[176:179], v[50:65]
	s_waitcnt lgkmcnt(0)
	v_mfma_f32_32x32x16_bf16 v[2:17], v[194:197], v[168:171], v[2:17]
	ds_read_b128 v[156:159], v0 offset:64
	ds_read_b128 v[160:163], v149 offset:36928
	ds_read_b128 v[164:167], v0 offset:96
	ds_read_b128 v[168:171], v149 offset:36960
	v_mfma_f32_32x32x16_bf16 v[18:33], v[194:197], v[176:179], v[18:33]
	ds_read_b128 v[172:175], v149 offset:41536
	ds_read_b128 v[176:179], v149 offset:41568
	s_waitcnt lgkmcnt(4)
	v_mfma_f32_32x32x16_bf16 v[98:113], v[156:159], v[160:163], v[98:113]
	s_waitcnt lgkmcnt(1)
	v_mfma_f32_32x32x16_bf16 v[114:129], v[156:159], v[172:175], v[114:129]
	ds_read_b128 v[156:159], v0 offset:4672
	ds_read_b128 v[186:189], v0 offset:4704
	s_waitcnt lgkmcnt(1)
	v_mfma_f32_32x32x16_bf16 v[66:81], v[156:159], v[160:163], v[66:81]
	v_mfma_f32_32x32x16_bf16 v[82:97], v[156:159], v[172:175], v[82:97]
	ds_read_b128 v[156:159], v0 offset:9280
	ds_read_b128 v[190:193], v0 offset:9312
	s_waitcnt lgkmcnt(1)
	v_mfma_f32_32x32x16_bf16 v[34:49], v[156:159], v[160:163], v[34:49]
	v_mfma_f32_32x32x16_bf16 v[50:65], v[156:159], v[172:175], v[50:65]
	ds_read_b128 v[156:159], v0 offset:13888
	ds_read_b128 v[194:197], v0 offset:13920
	s_waitcnt lgkmcnt(1)
	v_mfma_f32_32x32x16_bf16 v[2:17], v[156:159], v[160:163], v[2:17]
	v_mfma_f32_32x32x16_bf16 v[18:33], v[156:159], v[172:175], v[18:33]
	global_load_dwordx4 v[156:159], v[130:131], off offset:384
	global_load_dwordx4 v[160:163], v[132:133], off offset:384
	v_mfma_f32_32x32x16_bf16 v[98:113], v[164:167], v[168:171], v[98:113]
	v_mfma_f32_32x32x16_bf16 v[114:129], v[164:167], v[176:179], v[114:129]
	v_mfma_f32_32x32x16_bf16 v[66:81], v[186:189], v[168:171], v[66:81]
	v_mfma_f32_32x32x16_bf16 v[82:97], v[186:189], v[176:179], v[82:97]
	v_mfma_f32_32x32x16_bf16 v[34:49], v[190:193], v[168:171], v[34:49]
	v_mfma_f32_32x32x16_bf16 v[50:65], v[190:193], v[176:179], v[50:65]
	global_load_dwordx4 v[164:167], v[134:135], off offset:384
	global_load_dwordx4 v[172:175], v[136:137], off offset:384
	global_load_dwordx4 v[186:189], v[138:139], off offset:384
	global_load_dwordx4 v[190:193], v[140:141], off offset:384
	global_load_dwordx4 v[198:201], v[142:143], off offset:384
	global_load_dwordx4 v[202:205], v[144:145], off offset:384
	global_load_dwordx4 v[206:209], v[146:147], off offset:384
	global_load_dwordx4 v[210:213], v[150:151], off offset:384
	s_waitcnt lgkmcnt(0)
	v_mfma_f32_32x32x16_bf16 v[2:17], v[194:197], v[168:171], v[2:17]
	global_load_dwordx4 v[168:171], v[152:153], off offset:384
	global_load_dwordx4 v[236:239], v[154:155], off offset:384
	s_barrier
	s_waitcnt vmcnt(11)
	ds_write_b128 v148, v[156:159]
	s_waitcnt vmcnt(10)
	ds_write_b128 v148, v[160:163] offset:4608
	s_waitcnt vmcnt(9)
	ds_write_b128 v148, v[164:167] offset:9216
	s_waitcnt vmcnt(8)
	ds_write_b128 v148, v[172:175] offset:13824
	s_waitcnt vmcnt(7)
	ds_write_b128 v148, v[186:189] offset:18432
	s_waitcnt vmcnt(6)
	ds_write_b128 v148, v[190:193] offset:23040
	s_waitcnt vmcnt(5)
	ds_write_b128 v148, v[198:201] offset:27648
	s_waitcnt vmcnt(4)
	ds_write_b128 v148, v[202:205] offset:32256
	s_waitcnt vmcnt(3)
	ds_write_b128 v148, v[206:209] offset:36864
	s_waitcnt vmcnt(2)
	ds_write_b128 v148, v[210:213] offset:41472
	s_waitcnt vmcnt(1)
	ds_write_b128 v148, v[168:171] offset:46080
	s_waitcnt vmcnt(0)
	ds_write_b128 v148, v[236:239] offset:50688
	v_mfma_f32_32x32x16_bf16 v[18:33], v[194:197], v[176:179], v[18:33]
	s_waitcnt lgkmcnt(0)
	s_barrier
; #define MFMA32(a, b, c) __builtin_amdgcn_mfma_f32_32x32x16_bf16((a), (b), (c), 0, 0, 0)
; DI void gemm_mainloop_big(const bf16_t* __restrict__ A, int lda, const bf16_t* __restrict__ Bt, int ldb, int K, int m0, int n0,
;                           f32x16 (&acc)[4][2], char* smem) {
;     ...
;   for (int kt = 0; kt < nk; ++kt) {
;     if (kt + 1 < nk) {
; #pragma unroll
;       for (int i = 0; i < 8; ++i) ra[i] = *(const u32x4*)(ap + (size_t)(32 * i) * lda + (kt + 1) * 64);
; #pragma unroll
;       for (int i = 0; i < 4; ++i) rb[i] = *(const u32x4*)(bp + (size_t)(32 * i) * ldb + (kt + 1) * 64);
;     }
; #pragma unroll
;     for (int ks = 0; ks < 4; ++ks) {
;       bf16x8 af[4], bfr[2];
; #pragma unroll
;       for (int f = 0; f < 4; ++f) af[f] = *(const bf16x8*)&sa[wm * 128 + f * 32 + r][ks * 16 + half * 8];
; #pragma unroll
;       for (int f = 0; f < 2; ++f) bfr[f] = *(const bf16x8*)&sb[wn * 64 + f * 32 + r][ks * 16 + half * 8];
; #pragma unroll
;       for (int mf = 0; mf < 4; ++mf)
; #pragma unroll
;         for (int nf = 0; nf < 2; ++nf) acc[mf][nf] = MFMA32(af[mf], bfr[nf], acc[mf][nf]);
;     }
;     __syncthreads();
;     if (kt + 1 < nk) {
; #pragma unroll
;       for (int i = 0; i < 8; ++i) *(u32x4*)&sa[(tid >> 3) + 32 * i][(tid & 7) * 8] = ra[i];
; #pragma unroll
;       for (int i = 0; i < 4; ++i) *(u32x4*)&sb[(tid >> 3) + 32 * i][(tid & 7) * 8] = rb[i];
;     }
;     __syncthreads();
	ds_read_b128 v[156:159], v0
	ds_read_b128 v[160:163], v149 offset:36864
	ds_read_b128 v[164:167], v0 offset:32
	ds_read_b128 v[168:171], v149 offset:36896
	ds_read_b128 v[172:175], v149 offset:41472
	ds_read_b128 v[176:179], v149 offset:41504
	s_waitcnt lgkmcnt(4)
	v_mfma_f32_32x32x16_bf16 v[98:113], v[156:159], v[160:163], v[98:113]
	s_waitcnt lgkmcnt(1)
	v_mfma_f32_32x32x16_bf16 v[114:129], v[156:159], v[172:175], v[114:129]
	ds_read_b128 v[156:159], v0 offset:4608
	ds_read_b128 v[186:189], v0 offset:4640
	s_waitcnt lgkmcnt(1)
	v_mfma_f32_32x32x16_bf16 v[66:81], v[156:159], v[160:163], v[66:81]
	v_mfma_f32_32x32x16_bf16 v[82:97], v[156:159], v[172:175], v[82:97]
	ds_read_b128 v[156:159], v0 offset:9216
	ds_read_b128 v[190:193], v0 offset:9248
	s_waitcnt lgkmcnt(1)
	v_mfma_f32_32x32x16_bf16 v[34:49], v[156:159], v[160:163], v[34:49]
	v_mfma_f32_32x32x16_bf16 v[50:65], v[156:159], v[172:175], v[50:65]
	ds_read_b128 v[156:159], v0 offset:13824
	ds_read_b128 v[194:197], v0 offset:13856
	s_waitcnt lgkmcnt(1)
	v_mfma_f32_32x32x16_bf16 v[2:17], v[156:159], v[160:163], v[2:17]
	v_mfma_f32_32x32x16_bf16 v[18:33], v[156:159], v[172:175], v[18:33]
	v_mfma_f32_32x32x16_bf16 v[98:113], v[164:167], v[168:171], v[98:113]
	v_mfma_f32_32x32x16_bf16 v[114:129], v[164:167], v[176:179], v[114:129]
	v_mfma_f32_32x32x16_bf16 v[66:81], v[186:189], v[168:171], v[66:81]
	v_mfma_f32_32x32x16_bf16 v[82:97], v[186:189], v[176:179], v[82:97]
	v_mfma_f32_32x32x16_bf16 v[34:49], v[190:193], v[168:171], v[34:49]
	v_mfma_f32_32x32x16_bf16 v[50:65], v[190:193], v[176:179], v[50:65]
	s_waitcnt lgkmcnt(0)
	v_mfma_f32_32x32x16_bf16 v[2:17], v[194:197], v[168:171], v[2:17]
	ds_read_b128 v[156:159], v0 offset:64
	ds_read_b128 v[160:163], v149 offset:36928
	ds_read_b128 v[164:167], v0 offset:96
	ds_read_b128 v[168:171], v149 offset:36960
	v_mfma_f32_32x32x16_bf16 v[18:33], v[194:197], v[176:179], v[18:33]
	ds_read_b128 v[172:175], v149 offset:41536
	ds_read_b128 v[176:179], v149 offset:41568
	s_waitcnt lgkmcnt(4)
	v_mfma_f32_32x32x16_bf16 v[98:113], v[156:159], v[160:163], v[98:113]
	s_waitcnt lgkmcnt(1)
	v_mfma_f32_32x32x16_bf16 v[114:129], v[156:159], v[172:175], v[114:129]
	ds_read_b128 v[156:159], v0 offset:4672
	ds_read_b128 v[186:189], v0 offset:4704
	s_waitcnt lgkmcnt(1)
	v_mfma_f32_32x32x16_bf16 v[66:81], v[156:159], v[160:163], v[66:81]
	v_mfma_f32_32x32x16_bf16 v[82:97], v[156:159], v[172:175], v[82:97]
	ds_read_b128 v[156:159], v0 offset:9280
	ds_read_b128 v[190:193], v0 offset:9312
	s_waitcnt lgkmcnt(1)
	v_mfma_f32_32x32x16_bf16 v[34:49], v[156:159], v[160:163], v[34:49]
	v_mfma_f32_32x32x16_bf16 v[50:65], v[156:159], v[172:175], v[50:65]
	ds_read_b128 v[156:159], v0 offset:13888
	ds_read_b128 v[194:197], v0 offset:13920
	s_waitcnt lgkmcnt(1)
	v_mfma_f32_32x32x16_bf16 v[2:17], v[156:159], v[160:163], v[2:17]
	v_mfma_f32_32x32x16_bf16 v[18:33], v[156:159], v[172:175], v[18:33]
	global_load_dwordx4 v[156:159], v[130:131], off offset:512
	global_load_dwordx4 v[160:163], v[132:133], off offset:512
	v_mfma_f32_32x32x16_bf16 v[98:113], v[164:167], v[168:171], v[98:113]
	v_mfma_f32_32x32x16_bf16 v[114:129], v[164:167], v[176:179], v[114:129]
	v_mfma_f32_32x32x16_bf16 v[66:81], v[186:189], v[168:171], v[66:81]
	v_mfma_f32_32x32x16_bf16 v[82:97], v[186:189], v[176:179], v[82:97]
	v_mfma_f32_32x32x16_bf16 v[34:49], v[190:193], v[168:171], v[34:49]
	v_mfma_f32_32x32x16_bf16 v[50:65], v[190:193], v[176:179], v[50:65]
	global_load_dwordx4 v[164:167], v[134:135], off offset:512
	global_load_dwordx4 v[172:175], v[136:137], off offset:512
	global_load_dwordx4 v[186:189], v[138:139], off offset:512
	global_load_dwordx4 v[190:193], v[140:141], off offset:512
	global_load_dwordx4 v[198:201], v[142:143], off offset:512
	global_load_dwordx4 v[202:205], v[144:145], off offset:512
	global_load_dwordx4 v[206:209], v[146:147], off offset:512
	global_load_dwordx4 v[210:213], v[150:151], off offset:512
	s_waitcnt lgkmcnt(0)
	v_mfma_f32_32x32x16_bf16 v[2:17], v[194:197], v[168:171], v[2:17]
	global_load_dwordx4 v[168:171], v[152:153], off offset:512
	global_load_dwordx4 v[236:239], v[154:155], off offset:512
	s_barrier
	s_waitcnt vmcnt(11)
	ds_write_b128 v148, v[156:159]
	s_waitcnt vmcnt(10)
	ds_write_b128 v148, v[160:163] offset:4608
	s_waitcnt vmcnt(9)
	ds_write_b128 v148, v[164:167] offset:9216
	s_waitcnt vmcnt(8)
	ds_write_b128 v148, v[172:175] offset:13824
	s_waitcnt vmcnt(7)
	ds_write_b128 v148, v[186:189] offset:18432
	s_waitcnt vmcnt(6)
	ds_write_b128 v148, v[190:193] offset:23040
	s_waitcnt vmcnt(5)
	ds_write_b128 v148, v[198:201] offset:27648
	s_waitcnt vmcnt(4)
	ds_write_b128 v148, v[202:205] offset:32256
	s_waitcnt vmcnt(3)
	ds_write_b128 v148, v[206:209] offset:36864
	s_waitcnt vmcnt(2)
	ds_write_b128 v148, v[210:213] offset:41472
	s_waitcnt vmcnt(1)
	ds_write_b128 v148, v[168:171] offset:46080
	s_waitcnt vmcnt(0)
	ds_write_b128 v148, v[236:239] offset:50688
	v_mfma_f32_32x32x16_bf16 v[18:33], v[194:197], v[176:179], v[18:33]
	s_waitcnt lgkmcnt(0)
	s_barrier
; #define MFMA32(a, b, c) __builtin_amdgcn_mfma_f32_32x32x16_bf16((a), (b), (c), 0, 0, 0)
; DI void gemm_mainloop_big(const bf16_t* __restrict__ A, int lda, const bf16_t* __restrict__ Bt, int ldb, int K, int m0, int n0,
;                           f32x16 (&acc)[4][2], char* smem) {
;     ...
;   for (int kt = 0; kt < nk; ++kt) {
;     if (kt + 1 < nk) {
; #pragma unroll
;       for (int i = 0; i < 8; ++i) ra[i] = *(const u32x4*)(ap + (size_t)(32 * i) * lda + (kt + 1) * 64);
; #pragma unroll
;       for (int i = 0; i < 4; ++i) rb[i] = *(const u32x4*)(bp + (size_t)(32 * i) * ldb + (kt + 1) * 64);
;     }
; #pragma unroll
;     for (int ks = 0; ks < 4; ++ks) {
;       bf16x8 af[4], bfr[2];
; #pragma unroll
;       for (int f = 0; f < 4; ++f) af[f] = *(const bf16x8*)&sa[wm * 128 + f * 32 + r][ks * 16 + half * 8];
; #pragma unroll
;       for (int f = 0; f < 2; ++f) bfr[f] = *(const bf16x8*)&sb[wn * 64 + f * 32 + r][ks * 16 + half * 8];
; #pragma unroll
;       for (int mf = 0; mf < 4; ++mf)
; #pragma unroll
;         for (int nf = 0; nf < 2; ++nf) acc[mf][nf] = MFMA32(af[mf], bfr[nf], acc[mf][nf]);
;     }
;     __syncthreads();
;     if (kt + 1 < nk) {
; #pragma unroll
;       for (int i = 0; i < 8; ++i) *(u32x4*)&sa[(tid >> 3) + 32 * i][(tid & 7) * 8] = ra[i];
; #pragma unroll
;       for (int i = 0; i < 4; ++i) *(u32x4*)&sb[(tid >> 3) + 32 * i][(tid & 7) * 8] = rb[i];
;     }
;     __syncthreads();
	ds_read_b128 v[156:159], v0
	ds_read_b128 v[160:163], v149 offset:36864
	ds_read_b128 v[164:167], v0 offset:32
	ds_read_b128 v[168:171], v149 offset:36896
	ds_read_b128 v[172:175], v149 offset:41472
	ds_read_b128 v[176:179], v149 offset:41504
	s_waitcnt lgkmcnt(4)
	v_mfma_f32_32x32x16_bf16 v[98:113], v[156:159], v[160:163], v[98:113]
	s_waitcnt lgkmcnt(1)
	v_mfma_f32_32x32x16_bf16 v[114:129], v[156:159], v[172:175], v[114:129]
	ds_read_b128 v[156:159], v0 offset:4608
	ds_read_b128 v[186:189], v0 offset:4640
	s_waitcnt lgkmcnt(1)
	v_mfma_f32_32x32x16_bf16 v[66:81], v[156:159], v[160:163], v[66:81]
	v_mfma_f32_32x32x16_bf16 v[82:97], v[156:159], v[172:175], v[82:97]
	ds_read_b128 v[156:159], v0 offset:9216
	ds_read_b128 v[190:193], v0 offset:9248
	s_waitcnt lgkmcnt(1)
	v_mfma_f32_32x32x16_bf16 v[34:49], v[156:159], v[160:163], v[34:49]
	v_mfma_f32_32x32x16_bf16 v[50:65], v[156:159], v[172:175], v[50:65]
	ds_read_b128 v[156:159], v0 offset:13824
	ds_read_b128 v[194:197], v0 offset:13856
	s_waitcnt lgkmcnt(1)
	v_mfma_f32_32x32x16_bf16 v[2:17], v[156:159], v[160:163], v[2:17]
	v_mfma_f32_32x32x16_bf16 v[18:33], v[156:159], v[172:175], v[18:33]
	v_mfma_f32_32x32x16_bf16 v[98:113], v[164:167], v[168:171], v[98:113]
	v_mfma_f32_32x32x16_bf16 v[114:129], v[164:167], v[176:179], v[114:129]
	v_mfma_f32_32x32x16_bf16 v[66:81], v[186:189], v[168:171], v[66:81]
	v_mfma_f32_32x32x16_bf16 v[82:97], v[186:189], v[176:179], v[82:97]
	v_mfma_f32_32x32x16_bf16 v[34:49], v[190:193], v[168:171], v[34:49]
	v_mfma_f32_32x32x16_bf16 v[50:65], v[190:193], v[176:179], v[50:65]
	s_waitcnt lgkmcnt(0)
	v_mfma_f32_32x32x16_bf16 v[2:17], v[194:197], v[168:171], v[2:17]
	ds_read_b128 v[156:159], v0 offset:64
	ds_read_b128 v[160:163], v149 offset:36928
	ds_read_b128 v[164:167], v0 offset:96
	ds_read_b128 v[168:171], v149 offset:36960
	v_mfma_f32_32x32x16_bf16 v[18:33], v[194:197], v[176:179], v[18:33]
	ds_read_b128 v[172:175], v149 offset:41536
	ds_read_b128 v[176:179], v149 offset:41568
	s_waitcnt lgkmcnt(4)
	v_mfma_f32_32x32x16_bf16 v[98:113], v[156:159], v[160:163], v[98:113]
	s_waitcnt lgkmcnt(1)
	v_mfma_f32_32x32x16_bf16 v[114:129], v[156:159], v[172:175], v[114:129]
	ds_read_b128 v[156:159], v0 offset:4672
	ds_read_b128 v[186:189], v0 offset:4704
	s_waitcnt lgkmcnt(1)
	v_mfma_f32_32x32x16_bf16 v[66:81], v[156:159], v[160:163], v[66:81]
	v_mfma_f32_32x32x16_bf16 v[82:97], v[156:159], v[172:175], v[82:97]
	ds_read_b128 v[156:159], v0 offset:9280
	ds_read_b128 v[190:193], v0 offset:9312
	s_waitcnt lgkmcnt(1)
	v_mfma_f32_32x32x16_bf16 v[34:49], v[156:159], v[160:163], v[34:49]
	v_mfma_f32_32x32x16_bf16 v[50:65], v[156:159], v[172:175], v[50:65]
	ds_read_b128 v[156:159], v0 offset:13888
	ds_read_b128 v[194:197], v0 offset:13920
	s_waitcnt lgkmcnt(1)
	v_mfma_f32_32x32x16_bf16 v[2:17], v[156:159], v[160:163], v[2:17]
	v_mfma_f32_32x32x16_bf16 v[18:33], v[156:159], v[172:175], v[18:33]
	global_load_dwordx4 v[156:159], v[130:131], off offset:640
	global_load_dwordx4 v[160:163], v[132:133], off offset:640
	v_mfma_f32_32x32x16_bf16 v[98:113], v[164:167], v[168:171], v[98:113]
	v_mfma_f32_32x32x16_bf16 v[114:129], v[164:167], v[176:179], v[114:129]
	v_mfma_f32_32x32x16_bf16 v[66:81], v[186:189], v[168:171], v[66:81]
	v_mfma_f32_32x32x16_bf16 v[82:97], v[186:189], v[176:179], v[82:97]
	v_mfma_f32_32x32x16_bf16 v[34:49], v[190:193], v[168:171], v[34:49]
	v_mfma_f32_32x32x16_bf16 v[50:65], v[190:193], v[176:179], v[50:65]
	global_load_dwordx4 v[164:167], v[134:135], off offset:640
	global_load_dwordx4 v[172:175], v[136:137], off offset:640
	global_load_dwordx4 v[186:189], v[138:139], off offset:640
	global_load_dwordx4 v[190:193], v[140:141], off offset:640
	global_load_dwordx4 v[198:201], v[142:143], off offset:640
	global_load_dwordx4 v[202:205], v[144:145], off offset:640
	global_load_dwordx4 v[206:209], v[146:147], off offset:640
	global_load_dwordx4 v[210:213], v[150:151], off offset:640
	s_waitcnt lgkmcnt(0)
	v_mfma_f32_32x32x16_bf16 v[2:17], v[194:197], v[168:171], v[2:17]
	global_load_dwordx4 v[168:171], v[152:153], off offset:640
	global_load_dwordx4 v[236:239], v[154:155], off offset:640
	s_barrier
	s_waitcnt vmcnt(11)
	ds_write_b128 v148, v[156:159]
	s_waitcnt vmcnt(10)
	ds_write_b128 v148, v[160:163] offset:4608
	s_waitcnt vmcnt(9)
	ds_write_b128 v148, v[164:167] offset:9216
	s_waitcnt vmcnt(8)
	ds_write_b128 v148, v[172:175] offset:13824
	s_waitcnt vmcnt(7)
	ds_write_b128 v148, v[186:189] offset:18432
	s_waitcnt vmcnt(6)
	ds_write_b128 v148, v[190:193] offset:23040
	s_waitcnt vmcnt(5)
	ds_write_b128 v148, v[198:201] offset:27648
	s_waitcnt vmcnt(4)
	ds_write_b128 v148, v[202:205] offset:32256
	s_waitcnt vmcnt(3)
	ds_write_b128 v148, v[206:209] offset:36864
	s_waitcnt vmcnt(2)
	ds_write_b128 v148, v[210:213] offset:41472
	s_waitcnt vmcnt(1)
	ds_write_b128 v148, v[168:171] offset:46080
	s_waitcnt vmcnt(0)
	ds_write_b128 v148, v[236:239] offset:50688
	v_mfma_f32_32x32x16_bf16 v[18:33], v[194:197], v[176:179], v[18:33]
	s_waitcnt lgkmcnt(0)
	s_barrier
; #define MFMA32(a, b, c) __builtin_amdgcn_mfma_f32_32x32x16_bf16((a), (b), (c), 0, 0, 0)
; DI void gemm_mainloop_big(const bf16_t* __restrict__ A, int lda, const bf16_t* __restrict__ Bt, int ldb, int K, int m0, int n0,
;                           f32x16 (&acc)[4][2], char* smem) {
;     ...
;   for (int kt = 0; kt < nk; ++kt) {
;     if (kt + 1 < nk) {
; #pragma unroll
;       for (int i = 0; i < 8; ++i) ra[i] = *(const u32x4*)(ap + (size_t)(32 * i) * lda + (kt + 1) * 64);
; #pragma unroll
;       for (int i = 0; i < 4; ++i) rb[i] = *(const u32x4*)(bp + (size_t)(32 * i) * ldb + (kt + 1) * 64);
;     }
; #pragma unroll
;     for (int ks = 0; ks < 4; ++ks) {
;       bf16x8 af[4], bfr[2];
; #pragma unroll
;       for (int f = 0; f < 4; ++f) af[f] = *(const bf16x8*)&sa[wm * 128 + f * 32 + r][ks * 16 + half * 8];
; #pragma unroll
;       for (int f = 0; f < 2; ++f) bfr[f] = *(const bf16x8*)&sb[wn * 64 + f * 32 + r][ks * 16 + half * 8];
; #pragma unroll
;       for (int mf = 0; mf < 4; ++mf)
; #pragma unroll
;         for (int nf = 0; nf < 2; ++nf) acc[mf][nf] = MFMA32(af[mf], bfr[nf], acc[mf][nf]);
;     }
;     __syncthreads();
;     if (kt + 1 < nk) {
; #pragma unroll
;       for (int i = 0; i < 8; ++i) *(u32x4*)&sa[(tid >> 3) + 32 * i][(tid & 7) * 8] = ra[i];
; #pragma unroll
;       for (int i = 0; i < 4; ++i) *(u32x4*)&sb[(tid >> 3) + 32 * i][(tid & 7) * 8] = rb[i];
;     }
;     __syncthreads();
	ds_read_b128 v[156:159], v0
	ds_read_b128 v[160:163], v149 offset:36864
	ds_read_b128 v[164:167], v0 offset:32
	ds_read_b128 v[168:171], v149 offset:36896
	ds_read_b128 v[172:175], v149 offset:41472
	ds_read_b128 v[176:179], v149 offset:41504
	s_waitcnt lgkmcnt(4)
	v_mfma_f32_32x32x16_bf16 v[98:113], v[156:159], v[160:163], v[98:113]
	s_waitcnt lgkmcnt(1)
	v_mfma_f32_32x32x16_bf16 v[114:129], v[156:159], v[172:175], v[114:129]
	ds_read_b128 v[156:159], v0 offset:4608
	ds_read_b128 v[186:189], v0 offset:4640
	s_waitcnt lgkmcnt(1)
	v_mfma_f32_32x32x16_bf16 v[66:81], v[156:159], v[160:163], v[66:81]
	v_mfma_f32_32x32x16_bf16 v[82:97], v[156:159], v[172:175], v[82:97]
	ds_read_b128 v[156:159], v0 offset:9216
	ds_read_b128 v[190:193], v0 offset:9248
	s_waitcnt lgkmcnt(1)
	v_mfma_f32_32x32x16_bf16 v[34:49], v[156:159], v[160:163], v[34:49]
	v_mfma_f32_32x32x16_bf16 v[50:65], v[156:159], v[172:175], v[50:65]
	ds_read_b128 v[156:159], v0 offset:13824
	ds_read_b128 v[194:197], v0 offset:13856
	s_waitcnt lgkmcnt(1)
	v_mfma_f32_32x32x16_bf16 v[2:17], v[156:159], v[160:163], v[2:17]
	v_mfma_f32_32x32x16_bf16 v[18:33], v[156:159], v[172:175], v[18:33]
	v_mfma_f32_32x32x16_bf16 v[98:113], v[164:167], v[168:171], v[98:113]
	v_mfma_f32_32x32x16_bf16 v[114:129], v[164:167], v[176:179], v[114:129]
	v_mfma_f32_32x32x16_bf16 v[66:81], v[186:189], v[168:171], v[66:81]
	v_mfma_f32_32x32x16_bf16 v[82:97], v[186:189], v[176:179], v[82:97]
	v_mfma_f32_32x32x16_bf16 v[34:49], v[190:193], v[168:171], v[34:49]
	v_mfma_f32_32x32x16_bf16 v[50:65], v[190:193], v[176:179], v[50:65]
	s_waitcnt lgkmcnt(0)
	v_mfma_f32_32x32x16_bf16 v[2:17], v[194:197], v[168:171], v[2:17]
	ds_read_b128 v[156:159], v0 offset:64
	ds_read_b128 v[160:163], v149 offset:36928
	ds_read_b128 v[164:167], v0 offset:96
	ds_read_b128 v[168:171], v149 offset:36960
	v_mfma_f32_32x32x16_bf16 v[18:33], v[194:197], v[176:179], v[18:33]
	ds_read_b128 v[172:175], v149 offset:41536
	ds_read_b128 v[176:179], v149 offset:41568
	s_waitcnt lgkmcnt(4)
	v_mfma_f32_32x32x16_bf16 v[98:113], v[156:159], v[160:163], v[98:113]
	s_waitcnt lgkmcnt(1)
	v_mfma_f32_32x32x16_bf16 v[114:129], v[156:159], v[172:175], v[114:129]
	ds_read_b128 v[156:159], v0 offset:4672
	ds_read_b128 v[186:189], v0 offset:4704
	s_waitcnt lgkmcnt(1)
	v_mfma_f32_32x32x16_bf16 v[66:81], v[156:159], v[160:163], v[66:81]
	v_mfma_f32_32x32x16_bf16 v[82:97], v[156:159], v[172:175], v[82:97]
	ds_read_b128 v[156:159], v0 offset:9280
	ds_read_b128 v[190:193], v0 offset:9312
	s_waitcnt lgkmcnt(1)
	v_mfma_f32_32x32x16_bf16 v[34:49], v[156:159], v[160:163], v[34:49]
	v_mfma_f32_32x32x16_bf16 v[50:65], v[156:159], v[172:175], v[50:65]
	ds_read_b128 v[156:159], v0 offset:13888
	ds_read_b128 v[194:197], v0 offset:13920
	s_waitcnt lgkmcnt(1)
	v_mfma_f32_32x32x16_bf16 v[2:17], v[156:159], v[160:163], v[2:17]
	v_mfma_f32_32x32x16_bf16 v[18:33], v[156:159], v[172:175], v[18:33]
	global_load_dwordx4 v[156:159], v[130:131], off offset:768
	global_load_dwordx4 v[160:163], v[132:133], off offset:768
	v_mfma_f32_32x32x16_bf16 v[98:113], v[164:167], v[168:171], v[98:113]
	v_mfma_f32_32x32x16_bf16 v[114:129], v[164:167], v[176:179], v[114:129]
	v_mfma_f32_32x32x16_bf16 v[66:81], v[186:189], v[168:171], v[66:81]
	v_mfma_f32_32x32x16_bf16 v[82:97], v[186:189], v[176:179], v[82:97]
	v_mfma_f32_32x32x16_bf16 v[34:49], v[190:193], v[168:171], v[34:49]
	v_mfma_f32_32x32x16_bf16 v[50:65], v[190:193], v[176:179], v[50:65]
	global_load_dwordx4 v[164:167], v[134:135], off offset:768
	global_load_dwordx4 v[172:175], v[136:137], off offset:768
	global_load_dwordx4 v[186:189], v[138:139], off offset:768
	global_load_dwordx4 v[190:193], v[140:141], off offset:768
	global_load_dwordx4 v[198:201], v[142:143], off offset:768
	global_load_dwordx4 v[202:205], v[144:145], off offset:768
	global_load_dwordx4 v[206:209], v[146:147], off offset:768
	global_load_dwordx4 v[210:213], v[150:151], off offset:768
	s_waitcnt lgkmcnt(0)
	v_mfma_f32_32x32x16_bf16 v[2:17], v[194:197], v[168:171], v[2:17]
	global_load_dwordx4 v[168:171], v[152:153], off offset:768
	global_load_dwordx4 v[236:239], v[154:155], off offset:768
	s_barrier
	s_waitcnt vmcnt(11)
	ds_write_b128 v148, v[156:159]
	s_waitcnt vmcnt(10)
	ds_write_b128 v148, v[160:163] offset:4608
	s_waitcnt vmcnt(9)
	ds_write_b128 v148, v[164:167] offset:9216
	s_waitcnt vmcnt(8)
	ds_write_b128 v148, v[172:175] offset:13824
	s_waitcnt vmcnt(7)
	ds_write_b128 v148, v[186:189] offset:18432
	s_waitcnt vmcnt(6)
	ds_write_b128 v148, v[190:193] offset:23040
	s_waitcnt vmcnt(5)
	ds_write_b128 v148, v[198:201] offset:27648
	s_waitcnt vmcnt(4)
	ds_write_b128 v148, v[202:205] offset:32256
	s_waitcnt vmcnt(3)
	ds_write_b128 v148, v[206:209] offset:36864
	s_waitcnt vmcnt(2)
	ds_write_b128 v148, v[210:213] offset:41472
	s_waitcnt vmcnt(1)
	ds_write_b128 v148, v[168:171] offset:46080
	s_waitcnt vmcnt(0)
	ds_write_b128 v148, v[236:239] offset:50688
	v_mfma_f32_32x32x16_bf16 v[18:33], v[194:197], v[176:179], v[18:33]
	s_waitcnt lgkmcnt(0)
	s_barrier
; #define MFMA32(a, b, c) __builtin_amdgcn_mfma_f32_32x32x16_bf16((a), (b), (c), 0, 0, 0)
; DI void gemm_mainloop_big(const bf16_t* __restrict__ A, int lda, const bf16_t* __restrict__ Bt, int ldb, int K, int m0, int n0,
;                           f32x16 (&acc)[4][2], char* smem) {
;     ...
;   for (int kt = 0; kt < nk; ++kt) {
;     if (kt + 1 < nk) {
; #pragma unroll
;       for (int i = 0; i < 8; ++i) ra[i] = *(const u32x4*)(ap + (size_t)(32 * i) * lda + (kt + 1) * 64);
; #pragma unroll
;       for (int i = 0; i < 4; ++i) rb[i] = *(const u32x4*)(bp + (size_t)(32 * i) * ldb + (kt + 1) * 64);
;     }
; #pragma unroll
;     for (int ks = 0; ks < 4; ++ks) {
;       bf16x8 af[4], bfr[2];
; #pragma unroll
;       for (int f = 0; f < 4; ++f) af[f] = *(const bf16x8*)&sa[wm * 128 + f * 32 + r][ks * 16 + half * 8];
; #pragma unroll
;       for (int f = 0; f < 2; ++f) bfr[f] = *(const bf16x8*)&sb[wn * 64 + f * 32 + r][ks * 16 + half * 8];
; #pragma unroll
;       for (int mf = 0; mf < 4; ++mf)
; #pragma unroll
;         for (int nf = 0; nf < 2; ++nf) acc[mf][nf] = MFMA32(af[mf], bfr[nf], acc[mf][nf]);
;     }
;     __syncthreads();
;     if (kt + 1 < nk) {
; #pragma unroll
;       for (int i = 0; i < 8; ++i) *(u32x4*)&sa[(tid >> 3) + 32 * i][(tid & 7) * 8] = ra[i];
; #pragma unroll
;       for (int i = 0; i < 4; ++i) *(u32x4*)&sb[(tid >> 3) + 32 * i][(tid & 7) * 8] = rb[i];
;     }
;     __syncthreads();
	ds_read_b128 v[156:159], v0
	ds_read_b128 v[160:163], v149 offset:36864
	ds_read_b128 v[164:167], v0 offset:32
	ds_read_b128 v[168:171], v149 offset:36896
	ds_read_b128 v[172:175], v149 offset:41472
	ds_read_b128 v[176:179], v149 offset:41504
	s_waitcnt lgkmcnt(4)
	v_mfma_f32_32x32x16_bf16 v[98:113], v[156:159], v[160:163], v[98:113]
	s_waitcnt lgkmcnt(1)
	v_mfma_f32_32x32x16_bf16 v[114:129], v[156:159], v[172:175], v[114:129]
	ds_read_b128 v[156:159], v0 offset:4608
	ds_read_b128 v[186:189], v0 offset:4640
	s_waitcnt lgkmcnt(1)
	v_mfma_f32_32x32x16_bf16 v[66:81], v[156:159], v[160:163], v[66:81]
	v_mfma_f32_32x32x16_bf16 v[82:97], v[156:159], v[172:175], v[82:97]
	ds_read_b128 v[156:159], v0 offset:9216
	ds_read_b128 v[190:193], v0 offset:9248
	s_waitcnt lgkmcnt(1)
	v_mfma_f32_32x32x16_bf16 v[34:49], v[156:159], v[160:163], v[34:49]
	v_mfma_f32_32x32x16_bf16 v[50:65], v[156:159], v[172:175], v[50:65]
	ds_read_b128 v[156:159], v0 offset:13824
	ds_read_b128 v[194:197], v0 offset:13856
	s_waitcnt lgkmcnt(1)
	v_mfma_f32_32x32x16_bf16 v[2:17], v[156:159], v[160:163], v[2:17]
	v_mfma_f32_32x32x16_bf16 v[18:33], v[156:159], v[172:175], v[18:33]
	v_mfma_f32_32x32x16_bf16 v[98:113], v[164:167], v[168:171], v[98:113]
	v_mfma_f32_32x32x16_bf16 v[114:129], v[164:167], v[176:179], v[114:129]
	v_mfma_f32_32x32x16_bf16 v[66:81], v[186:189], v[168:171], v[66:81]
	v_mfma_f32_32x32x16_bf16 v[82:97], v[186:189], v[176:179], v[82:97]
	v_mfma_f32_32x32x16_bf16 v[34:49], v[190:193], v[168:171], v[34:49]
	v_mfma_f32_32x32x16_bf16 v[50:65], v[190:193], v[176:179], v[50:65]
	s_waitcnt lgkmcnt(0)
	v_mfma_f32_32x32x16_bf16 v[2:17], v[194:197], v[168:171], v[2:17]
	ds_read_b128 v[156:159], v0 offset:64
	ds_read_b128 v[160:163], v149 offset:36928
	ds_read_b128 v[164:167], v0 offset:96
	ds_read_b128 v[168:171], v149 offset:36960
	v_mfma_f32_32x32x16_bf16 v[18:33], v[194:197], v[176:179], v[18:33]
	ds_read_b128 v[172:175], v149 offset:41536
	ds_read_b128 v[176:179], v149 offset:41568
	s_waitcnt lgkmcnt(4)
	v_mfma_f32_32x32x16_bf16 v[98:113], v[156:159], v[160:163], v[98:113]
	s_waitcnt lgkmcnt(1)
	v_mfma_f32_32x32x16_bf16 v[114:129], v[156:159], v[172:175], v[114:129]
	ds_read_b128 v[156:159], v0 offset:4672
	ds_read_b128 v[186:189], v0 offset:4704
	s_waitcnt lgkmcnt(1)
	v_mfma_f32_32x32x16_bf16 v[66:81], v[156:159], v[160:163], v[66:81]
	v_mfma_f32_32x32x16_bf16 v[82:97], v[156:159], v[172:175], v[82:97]
	ds_read_b128 v[156:159], v0 offset:9280
	ds_read_b128 v[190:193], v0 offset:9312
	s_waitcnt lgkmcnt(1)
	v_mfma_f32_32x32x16_bf16 v[34:49], v[156:159], v[160:163], v[34:49]
	v_mfma_f32_32x32x16_bf16 v[50:65], v[156:159], v[172:175], v[50:65]
	ds_read_b128 v[156:159], v0 offset:13888
	ds_read_b128 v[194:197], v0 offset:13920
	s_waitcnt lgkmcnt(1)
	v_mfma_f32_32x32x16_bf16 v[2:17], v[156:159], v[160:163], v[2:17]
	v_mfma_f32_32x32x16_bf16 v[18:33], v[156:159], v[172:175], v[18:33]
	global_load_dwordx4 v[156:159], v[130:131], off offset:896
	s_nop 0
	global_load_dwordx4 v[130:133], v[132:133], off offset:896
	v_mfma_f32_32x32x16_bf16 v[98:113], v[164:167], v[168:171], v[98:113]
	v_mfma_f32_32x32x16_bf16 v[114:129], v[164:167], v[176:179], v[114:129]
	v_mfma_f32_32x32x16_bf16 v[66:81], v[186:189], v[168:171], v[66:81]
	v_mfma_f32_32x32x16_bf16 v[82:97], v[186:189], v[176:179], v[82:97]
	v_mfma_f32_32x32x16_bf16 v[34:49], v[190:193], v[168:171], v[34:49]
	v_mfma_f32_32x32x16_bf16 v[50:65], v[190:193], v[176:179], v[50:65]
	global_load_dwordx4 v[160:163], v[134:135], off offset:896
	s_nop 0
	global_load_dwordx4 v[134:137], v[136:137], off offset:896
	s_nop 0
	global_load_dwordx4 v[164:167], v[138:139], off offset:896
	s_nop 0
	global_load_dwordx4 v[138:141], v[140:141], off offset:896
	s_nop 0
	global_load_dwordx4 v[172:175], v[142:143], off offset:896
	s_nop 0
	global_load_dwordx4 v[142:145], v[144:145], off offset:896
	s_nop 0
	global_load_dwordx4 v[186:189], v[146:147], off offset:896
	global_load_dwordx4 v[190:193], v[150:151], off offset:896
	s_waitcnt lgkmcnt(0)
	v_mfma_f32_32x32x16_bf16 v[2:17], v[194:197], v[168:171], v[2:17]
	global_load_dwordx4 v[150:153], v[152:153], off offset:896
	s_nop 0
	global_load_dwordx4 v[168:171], v[154:155], off offset:896
	s_barrier
	s_waitcnt vmcnt(11)
	ds_write_b128 v148, v[156:159]
	s_waitcnt vmcnt(10)
	ds_write_b128 v148, v[130:133] offset:4608
	s_waitcnt vmcnt(9)
	ds_write_b128 v148, v[160:163] offset:9216
	s_waitcnt vmcnt(8)
	ds_write_b128 v148, v[134:137] offset:13824
	s_waitcnt vmcnt(7)
	ds_write_b128 v148, v[164:167] offset:18432
	s_waitcnt vmcnt(6)
	ds_write_b128 v148, v[138:141] offset:23040
	s_waitcnt vmcnt(5)
	ds_write_b128 v148, v[172:175] offset:27648
	s_waitcnt vmcnt(4)
	ds_write_b128 v148, v[142:145] offset:32256
	s_waitcnt vmcnt(3)
	ds_write_b128 v148, v[186:189] offset:36864
	s_waitcnt vmcnt(2)
	ds_write_b128 v148, v[190:193] offset:41472
	s_waitcnt vmcnt(1)
	ds_write_b128 v148, v[150:153] offset:46080
	s_waitcnt vmcnt(0)
	ds_write_b128 v148, v[168:171] offset:50688
	s_waitcnt lgkmcnt(0)
	s_barrier
; #define MFMA32(a, b, c) __builtin_amdgcn_mfma_f32_32x32x16_bf16((a), (b), (c), 0, 0, 0)
; DI void gemm_mainloop_big(const bf16_t* __restrict__ A, int lda, const bf16_t* __restrict__ Bt, int ldb, int K, int m0, int n0,
;                           f32x16 (&acc)[4][2], char* smem) {
;     ...
; #pragma unroll
;     for (int ks = 0; ks < 4; ++ks) {
;       bf16x8 af[4], bfr[2];
; #pragma unroll
;       for (int f = 0; f < 4; ++f) af[f] = *(const bf16x8*)&sa[wm * 128 + f * 32 + r][ks * 16 + half * 8];
; #pragma unroll
;       for (int f = 0; f < 2; ++f) bfr[f] = *(const bf16x8*)&sb[wn * 64 + f * 32 + r][ks * 16 + half * 8];
; #pragma unroll
;       for (int mf = 0; mf < 4; ++mf)
; #pragma unroll
;         for (int nf = 0; nf < 2; ++nf) acc[mf][nf] = MFMA32(af[mf], bfr[nf], acc[mf][nf]);
;     }
;     __syncthreads();
;     if (kt + 1 < nk) {
; #pragma unroll
;       for (int i = 0; i < 8; ++i) *(u32x4*)&sa[(tid >> 3) + 32 * i][(tid & 7) * 8] = ra[i];
; #pragma unroll
;       for (int i = 0; i < 4; ++i) *(u32x4*)&sb[(tid >> 3) + 32 * i][(tid & 7) * 8] = rb[i];
;     }
;     __syncthreads();
; DI void stage_half(float* st, const f32x16 (&acc)[4][2], int h, int tid) {
;   const int lane = tid & 63, w = tid >> 6, wm = w >> 1, wn = w & 1, c = lane & 31, half = lane >> 5;
;   if (wm == h) {
	ds_read_b128 v[130:133], v0
	ds_read_b128 v[134:137], v149 offset:36864
	ds_read_b128 v[138:141], v0 offset:32
	ds_read_b128 v[142:145], v149 offset:36896
	ds_read_b128 v[150:153], v149 offset:41472
	ds_read_b128 v[154:157], v149 offset:41504
	s_waitcnt lgkmcnt(4)
	v_mfma_f32_32x32x16_bf16 v[98:113], v[130:133], v[134:137], v[98:113]
	s_waitcnt lgkmcnt(1)
	v_mfma_f32_32x32x16_bf16 v[114:129], v[130:133], v[150:153], v[114:129]
	ds_read_b128 v[130:133], v0 offset:4608
	ds_read_b128 v[158:161], v0 offset:4640
	s_waitcnt lgkmcnt(1)
	v_mfma_f32_32x32x16_bf16 v[66:81], v[130:133], v[134:137], v[66:81]
	v_mfma_f32_32x32x16_bf16 v[82:97], v[130:133], v[150:153], v[82:97]
	ds_read_b128 v[130:133], v0 offset:9216
	ds_read_b128 v[162:165], v0 offset:9248
	v_mfma_f32_32x32x16_bf16 v[18:33], v[194:197], v[176:179], v[18:33]
	s_waitcnt lgkmcnt(1)
	v_mfma_f32_32x32x16_bf16 v[34:49], v[130:133], v[134:137], v[34:49]
	v_mfma_f32_32x32x16_bf16 v[50:65], v[130:133], v[150:153], v[50:65]
	ds_read_b128 v[130:133], v0 offset:13824
	ds_read_b128 v[166:169], v0 offset:13856
	s_waitcnt lgkmcnt(1)
	v_mfma_f32_32x32x16_bf16 v[2:17], v[130:133], v[134:137], v[2:17]
	v_mfma_f32_32x32x16_bf16 v[18:33], v[130:133], v[150:153], v[18:33]
	v_mfma_f32_32x32x16_bf16 v[98:113], v[138:141], v[142:145], v[98:113]
	v_mfma_f32_32x32x16_bf16 v[114:129], v[138:141], v[154:157], v[114:129]
	v_mfma_f32_32x32x16_bf16 v[66:81], v[158:161], v[142:145], v[66:81]
	v_mfma_f32_32x32x16_bf16 v[82:97], v[158:161], v[154:157], v[82:97]
	v_mfma_f32_32x32x16_bf16 v[34:49], v[162:165], v[142:145], v[34:49]
	s_waitcnt lgkmcnt(0)
	v_mfma_f32_32x32x16_bf16 v[2:17], v[166:169], v[142:145], v[2:17]
	ds_read_b128 v[130:133], v0 offset:64
	ds_read_b128 v[134:137], v149 offset:36928
	ds_read_b128 v[138:141], v0 offset:96
	ds_read_b128 v[142:145], v149 offset:36960
	ds_read_b128 v[150:153], v149 offset:41536
	ds_read_b128 v[146:149], v149 offset:41568
	v_mfma_f32_32x32x16_bf16 v[50:65], v[162:165], v[154:157], v[50:65]
	v_mfma_f32_32x32x16_bf16 v[18:33], v[166:169], v[154:157], v[18:33]
	s_waitcnt lgkmcnt(4)
	v_mfma_f32_32x32x16_bf16 v[98:113], v[130:133], v[134:137], v[98:113]
	s_waitcnt lgkmcnt(1)
	v_mfma_f32_32x32x16_bf16 v[114:129], v[130:133], v[150:153], v[114:129]
	ds_read_b128 v[130:133], v0 offset:4672
	ds_read_b128 v[154:157], v0 offset:4704
	s_waitcnt lgkmcnt(1)
	v_mfma_f32_32x32x16_bf16 v[66:81], v[130:133], v[134:137], v[66:81]
	v_mfma_f32_32x32x16_bf16 v[82:97], v[130:133], v[150:153], v[82:97]
	ds_read_b128 v[130:133], v0 offset:9280
	ds_read_b128 v[158:161], v0 offset:9312
	s_waitcnt lgkmcnt(1)
	v_mfma_f32_32x32x16_bf16 v[34:49], v[130:133], v[134:137], v[34:49]
	v_mfma_f32_32x32x16_bf16 v[50:65], v[130:133], v[150:153], v[50:65]
	ds_read_b128 v[130:133], v0 offset:13888
	ds_read_b128 v[162:165], v0 offset:13920
	v_mov_b32_e32 v0, v216
	s_waitcnt lgkmcnt(0)
	s_barrier
	s_barrier
	v_mfma_f32_32x32x16_bf16 v[2:17], v[130:133], v[134:137], v[2:17]
	s_nop 0
	v_cmp_gt_u32_e32 vcc, s31, v0
	v_mfma_f32_32x32x16_bf16 v[18:33], v[130:133], v[150:153], v[18:33]
	v_mfma_f32_32x32x16_bf16 v[98:113], v[138:141], v[142:145], v[98:113]
	v_mfma_f32_32x32x16_bf16 v[114:129], v[138:141], v[146:149], v[114:129]
	v_mfma_f32_32x32x16_bf16 v[66:81], v[154:157], v[142:145], v[66:81]
	v_mfma_f32_32x32x16_bf16 v[82:97], v[154:157], v[146:149], v[82:97]
	v_mfma_f32_32x32x16_bf16 v[34:49], v[158:161], v[142:145], v[34:49]
	v_mfma_f32_32x32x16_bf16 v[50:65], v[158:161], v[146:149], v[50:65]
	v_mfma_f32_32x32x16_bf16 v[2:17], v[162:165], v[142:145], v[2:17]
	v_mfma_f32_32x32x16_bf16 v[18:33], v[162:165], v[146:149], v[18:33]
	s_and_saveexec_b64 s[42:43], vcc
	s_cbranch_execz .LBB0_1054
; DI int crow(int i, int h) { return (i & 3) + 8 * (i >> 2) + 4 * h; }
; DI void stage_half(float* st, const f32x16 (&acc)[4][2], int h, int tid) {
;   const int lane = tid & 63, w = tid >> 6, wm = w >> 1, wn = w & 1, c = lane & 31, half = lane >> 5;
;   if (wm == h) {
; #pragma unroll
;     for (int mf = 0; mf < 4; ++mf)
; #pragma unroll
;       for (int nf = 0; nf < 2; ++nf)
; #pragma unroll
;         for (int i = 0; i < 16; ++i) st[(mf * 32 + crow(i, half)) * 132 + wn * 64 + nf * 32 + c] = acc[mf][nf][i];
;   }
; }
	v_lshrrev_b32_e32 v130, 3, v0
	v_and_b32_e32 v130, 4, v130
	v_and_b32_e32 v131, 0x5f, v0
	v_mul_u32_u24_e32 v130, 0x210, v130
	v_lshl_add_u32 v130, v131, 2, v130
	v_add_u32_e32 v131, 0x400, v130
	ds_write2_b32 v130, v98, v114 offset1:32
	ds_write2_b32 v130, v99, v115 offset0:132 offset1:164
	ds_write2_b32 v131, v100, v116 offset0:8 offset1:40
	ds_write2_b32 v131, v101, v117 offset0:140 offset1:172
	v_add_u32_e32 v131, 0x1000, v130
	ds_write2_b32 v131, v102, v118 offset0:32 offset1:64
	ds_write2_b32 v131, v103, v119 offset0:164 offset1:196
	v_add_u32_e32 v131, 0x1400, v130
	ds_write2_b32 v131, v104, v120 offset0:40 offset1:72
	ds_write2_b32 v131, v105, v121 offset0:172 offset1:204
	v_add_u32_e32 v131, 0x2000, v130
	ds_write2_b32 v131, v106, v122 offset0:64 offset1:96
	ds_write2_b32 v131, v107, v123 offset0:196 offset1:228
	v_add_u32_e32 v131, 0x2400, v130
	ds_write2_b32 v131, v108, v124 offset0:72 offset1:104
	ds_write2_b32 v131, v109, v125 offset0:204 offset1:236
	v_add_u32_e32 v131, 0x3000, v130
	ds_write2_b32 v131, v110, v126 offset0:96 offset1:128
	v_add_u32_e32 v131, 0x3200, v130
	ds_write2_b32 v131, v111, v127 offset0:100 offset1:132
	v_add_u32_e32 v131, 0x3400, v130
	ds_write2_b32 v131, v112, v128 offset0:104 offset1:136
	v_add_u32_e32 v131, 0x3600, v130
	ds_write2_b32 v131, v113, v129 offset0:108 offset1:140
	v_add_u32_e32 v131, 0x4000, v130
	ds_write2_b32 v131, v66, v82 offset0:128 offset1:160
	v_add_u32_e32 v131, 0x4400, v130
	ds_write2_b32 v131, v67, v83 offset0:4 offset1:36
	ds_write2_b32 v131, v68, v84 offset0:136 offset1:168
	v_add_u32_e32 v131, 0x4800, v130
	ds_write2_b32 v131, v69, v85 offset0:12 offset1:44
	v_add_u32_e32 v131, 0x5000, v130
	ds_write2_b32 v131, v70, v86 offset0:160 offset1:192
	v_add_u32_e32 v131, 0x5400, v130
	ds_write2_b32 v131, v71, v87 offset0:36 offset1:68
	ds_write2_b32 v131, v72, v88 offset0:168 offset1:200
	v_add_u32_e32 v131, 0x5800, v130
	ds_write2_b32 v131, v73, v89 offset0:44 offset1:76
	v_add_u32_e32 v131, 0x6000, v130
	ds_write2_b32 v131, v74, v90 offset0:192 offset1:224
	v_add_u32_e32 v131, 0x6400, v130
	ds_write2_b32 v131, v75, v91 offset0:68 offset1:100
	ds_write2_b32 v131, v76, v92 offset0:200 offset1:232
	v_add_u32_e32 v131, 0x6800, v130
	ds_write2_b32 v131, v77, v93 offset0:76 offset1:108
	v_add_u32_e32 v131, 0x7200, v130
	ds_write2_b32 v131, v78, v94 offset0:96 offset1:128
	v_add_u32_e32 v131, 0x7400, v130
	ds_write2_b32 v131, v79, v95 offset0:100 offset1:132
	v_add_u32_e32 v131, 0x7600, v130
	ds_write2_b32 v131, v80, v96 offset0:104 offset1:136
	v_add_u32_e32 v131, 0x7800, v130
	ds_write2_b32 v131, v81, v97 offset0:108 offset1:140
	v_add_u32_e32 v131, 0x8400, v130
	ds_write2_b32 v131, v34, v50 offset1:32
	ds_write2_b32 v131, v35, v51 offset0:132 offset1:164
	v_add_u32_e32 v131, 0x8800, v130
	ds_write2_b32 v131, v36, v52 offset0:8 offset1:40
	ds_write2_b32 v131, v37, v53 offset0:140 offset1:172
	v_add_u32_e32 v131, 0x9400, v130
	ds_write2_b32 v131, v38, v54 offset0:32 offset1:64
	ds_write2_b32 v131, v39, v55 offset0:164 offset1:196
	v_add_u32_e32 v131, 0x9800, v130
	ds_write2_b32 v131, v40, v56 offset0:40 offset1:72
	ds_write2_b32 v131, v41, v57 offset0:172 offset1:204
	v_add_u32_e32 v131, 0xa400, v130
	ds_write2_b32 v131, v42, v58 offset0:64 offset1:96
	ds_write2_b32 v131, v43, v59 offset0:196 offset1:228
	v_add_u32_e32 v131, 0xa800, v130
	ds_write2_b32 v131, v44, v60 offset0:72 offset1:104
	ds_write2_b32 v131, v45, v61 offset0:204 offset1:236
	v_add_u32_e32 v131, 0xb400, v130
	ds_write2_b32 v131, v46, v62 offset0:96 offset1:128
	v_add_u32_e32 v131, 0xb600, v130
	ds_write2_b32 v131, v47, v63 offset0:100 offset1:132
	v_add_u32_e32 v131, 0xb800, v130
	ds_write2_b32 v131, v48, v64 offset0:104 offset1:136
	v_add_u32_e32 v131, 0xba00, v130
	ds_write2_b32 v131, v49, v65 offset0:108 offset1:140
	v_add_u32_e32 v131, 0xc400, v130
	ds_write2_b32 v131, v2, v18 offset0:128 offset1:160
	v_add_u32_e32 v131, 0xc800, v130
	ds_write2_b32 v131, v3, v19 offset0:4 offset1:36
	ds_write2_b32 v131, v4, v20 offset0:136 offset1:168
	v_add_u32_e32 v131, 0xcc00, v130
	ds_write2_b32 v131, v5, v21 offset0:12 offset1:44
	v_add_u32_e32 v131, 0xd400, v130
	ds_write2_b32 v131, v6, v22 offset0:160 offset1:192
	v_add_u32_e32 v131, 0xd800, v130
	ds_write2_b32 v131, v7, v23 offset0:36 offset1:68
	ds_write2_b32 v131, v8, v24 offset0:168 offset1:200
	v_add_u32_e32 v131, 0xdc00, v130
	ds_write2_b32 v131, v9, v25 offset0:44 offset1:76
	v_add_u32_e32 v131, 0xe400, v130
	ds_write2_b32 v131, v10, v26 offset0:192 offset1:224
	v_add_u32_e32 v131, 0xe800, v130
	ds_write2_b32 v131, v11, v27 offset0:68 offset1:100
	ds_write2_b32 v131, v12, v28 offset0:200 offset1:232
	v_add_u32_e32 v131, 0xec00, v130
	ds_write2_b32 v131, v13, v29 offset0:76 offset1:108
	v_add_u32_e32 v131, 0xf600, v130
	ds_write2_b32 v131, v14, v30 offset0:96 offset1:128
	v_add_u32_e32 v131, 0xf800, v130
	ds_write2_b32 v131, v15, v31 offset0:100 offset1:132
	v_add_u32_e32 v131, 0xfa00, v130
	v_add_u32_e32 v130, 0xfc00, v130
	ds_write2_b32 v131, v16, v32 offset0:104 offset1:136
	ds_write2_b32 v130, v17, v33 offset0:108 offset1:140

; DI unsigned pk2(float a, float b) { f32x2 v = {a, b}; bf2_t r = __builtin_convertvector(v, bf2_t); return __builtin_bit_cast(unsigned, r); }
; DI float bf_lo(unsigned u) { return __uint_as_float(u << 16); }
; DI float bf_hi(unsigned u) { return __uint_as_float(u & 0xffff0000u); }
; DI void gemm_up_pass_big(const bf16_t* Y, const bf16_t* W, const bf16_t* __restrict__ GBR, int gcol0, bf16_t* __restrict__ MG, bool first,
;                          int mt, int nt, char* smem) {
;     ...
;     const int r = tid >> 4, ch = tid & 15;
; #pragma unroll 2
;     for (int ps = 0; ps < 8; ++ps) {
;       const int row = ps * 16 + r;
;       const float4 a0 = *(const float4*)(st + row * 132 + ch * 8), a1 = *(const float4*)(st + row * 132 + ch * 8 + 4);
;       const size_t grow = (size_t)(m0 + h * 128 + row);
;       const u32x4 gv = *(const u32x4*)(GBR + grow * 2048 + gcol0 + n0 + ch * 8);
;       float v[8];
;       v[0] = bf_lo(gv.x) * a0.x; v[1] = bf_hi(gv.x) * a0.y; v[2] = bf_lo(gv.y) * a0.z; v[3] = bf_hi(gv.y) * a0.w;
;       v[4] = bf_lo(gv.z) * a1.x; v[5] = bf_hi(gv.z) * a1.y; v[6] = bf_lo(gv.w) * a1.z; v[7] = bf_hi(gv.w) * a1.w;
;       bf16_t* mp = MG + grow * 1024 + n0 + ch * 8;
;       if (!first) {
;         const u32x4 pv = *(const u32x4*)mp;
;         v[0] += bf_lo(pv.x); v[1] += bf_hi(pv.x); v[2] += bf_lo(pv.y); v[3] += bf_hi(pv.y);
;         v[4] += bf_lo(pv.z); v[5] += bf_hi(pv.z); v[6] += bf_lo(pv.w); v[7] += bf_hi(pv.w);
;       }
;       u32x4 ov; ov.x = pk2(v[0], v[1]); ov.y = pk2(v[2], v[3]); ov.z = pk2(v[4], v[5]); ov.w = pk2(v[6], v[7]);
;       *(u32x4*)mp = ov;
;     }
.LBB0_1055:
	v_lshl_add_u64 v[194:195], v[136:137], 0, s[28:29]
	v_lshl_add_u64 v[196:197], v[132:133], 0, s[28:29]
	v_lshl_add_u64 v[202:203], v[134:135], 0, s[28:29]
	v_lshl_add_u64 v[204:205], v[130:131], 0, s[28:29]
	v_lshl_add_u64 v[198:199], v[134:135], 0, s[28:29]
	v_lshl_add_u64 v[200:201], v[130:131], 0, s[28:29]
	global_load_dwordx4 v[138:141], v[194:195], off
	global_load_dwordx4 v[154:157], v[198:199], off
	v_lshl_add_u64 v[194:195], v[194:195], 0, s[92:93]
	v_lshl_add_u64 v[198:199], v[198:199], 0, s[38:39]
	global_load_dwordx4 v[142:145], v[196:197], off
	global_load_dwordx4 v[158:161], v[200:201], off
	v_lshl_add_u64 v[196:197], v[196:197], 0, s[92:93]
	v_lshl_add_u64 v[200:201], v[200:201], 0, s[38:39]
	global_load_dwordx4 v[146:149], v[194:195], off
	global_load_dwordx4 v[162:165], v[198:199], off
	v_lshl_add_u64 v[194:195], v[194:195], 0, s[92:93]
	v_lshl_add_u64 v[198:199], v[198:199], 0, s[38:39]
	global_load_dwordx4 v[150:153], v[196:197], off
	global_load_dwordx4 v[166:169], v[200:201], off
	v_lshl_add_u64 v[196:197], v[196:197], 0, s[92:93]
	v_lshl_add_u64 v[200:201], v[200:201], 0, s[38:39]
	ds_read_b128 v[172:175], v0 offset:0
	ds_read_b128 v[176:179], v0 offset:16
	s_waitcnt vmcnt(6) lgkmcnt(0)
	v_lshlrev_b32_e32 v190, 16, v138
	v_and_b32_e32 v191, 0xffff0000, v138
	v_lshlrev_b32_e32 v192, 16, v154
	v_and_b32_e32 v193, 0xffff0000, v154
	v_pk_fma_f32 v[172:173], v[172:173], v[190:191], v[192:193]
	v_lshlrev_b32_e32 v190, 16, v139
	v_and_b32_e32 v191, 0xffff0000, v139
	v_lshlrev_b32_e32 v192, 16, v155
	v_and_b32_e32 v193, 0xffff0000, v155
	v_pk_fma_f32 v[174:175], v[174:175], v[190:191], v[192:193]
	v_lshlrev_b32_e32 v190, 16, v140
	v_and_b32_e32 v191, 0xffff0000, v140
	v_lshlrev_b32_e32 v192, 16, v156
	v_and_b32_e32 v193, 0xffff0000, v156
	v_pk_fma_f32 v[176:177], v[176:177], v[190:191], v[192:193]
	v_lshlrev_b32_e32 v190, 16, v141
	v_and_b32_e32 v191, 0xffff0000, v141
	v_lshlrev_b32_e32 v192, 16, v157
	v_and_b32_e32 v193, 0xffff0000, v157
	v_pk_fma_f32 v[178:179], v[178:179], v[190:191], v[192:193]
	v_cvt_pk_bf16_f32 v186, v172, v173
	v_cvt_pk_bf16_f32 v187, v174, v175
	v_cvt_pk_bf16_f32 v188, v176, v177
	v_cvt_pk_bf16_f32 v189, v178, v179
	global_store_dwordx4 v[202:203], v[186:189], off
	s_nop 1
	v_lshl_add_u64 v[202:203], v[202:203], 0, s[38:39]
	global_load_dwordx4 v[138:141], v[194:195], off
	global_load_dwordx4 v[154:157], v[198:199], off
	v_lshl_add_u64 v[194:195], v[194:195], 0, s[92:93]
	v_lshl_add_u64 v[198:199], v[198:199], 0, s[38:39]
	ds_read_b128 v[172:175], v0 offset:8448
	ds_read_b128 v[176:179], v0 offset:8464
	s_waitcnt vmcnt(7) lgkmcnt(0)
	v_lshlrev_b32_e32 v190, 16, v142
	v_and_b32_e32 v191, 0xffff0000, v142
	v_lshlrev_b32_e32 v192, 16, v158
	v_and_b32_e32 v193, 0xffff0000, v158
	v_pk_fma_f32 v[172:173], v[172:173], v[190:191], v[192:193]
	v_lshlrev_b32_e32 v190, 16, v143
	v_and_b32_e32 v191, 0xffff0000, v143
	v_lshlrev_b32_e32 v192, 16, v159
	v_and_b32_e32 v193, 0xffff0000, v159
	v_pk_fma_f32 v[174:175], v[174:175], v[190:191], v[192:193]
	v_lshlrev_b32_e32 v190, 16, v144
	v_and_b32_e32 v191, 0xffff0000, v144
	v_lshlrev_b32_e32 v192, 16, v160
	v_and_b32_e32 v193, 0xffff0000, v160
	v_pk_fma_f32 v[176:177], v[176:177], v[190:191], v[192:193]
	v_lshlrev_b32_e32 v190, 16, v145
	v_and_b32_e32 v191, 0xffff0000, v145
	v_lshlrev_b32_e32 v192, 16, v161
	v_and_b32_e32 v193, 0xffff0000, v161
	v_pk_fma_f32 v[178:179], v[178:179], v[190:191], v[192:193]
	v_cvt_pk_bf16_f32 v186, v172, v173
	v_cvt_pk_bf16_f32 v187, v174, v175
	v_cvt_pk_bf16_f32 v188, v176, v177
	v_cvt_pk_bf16_f32 v189, v178, v179
	global_store_dwordx4 v[204:205], v[186:189], off
	s_nop 1
	v_lshl_add_u64 v[204:205], v[204:205], 0, s[38:39]
	global_load_dwordx4 v[142:145], v[196:197], off
	global_load_dwordx4 v[158:161], v[200:201], off
	v_lshl_add_u64 v[196:197], v[196:197], 0, s[92:93]
	v_lshl_add_u64 v[200:201], v[200:201], 0, s[38:39]
	ds_read_b128 v[172:175], v0 offset:16896
	ds_read_b128 v[176:179], v0 offset:16912
	s_waitcnt vmcnt(8) lgkmcnt(0)
	v_lshlrev_b32_e32 v190, 16, v146
	v_and_b32_e32 v191, 0xffff0000, v146
	v_lshlrev_b32_e32 v192, 16, v162
	v_and_b32_e32 v193, 0xffff0000, v162
	v_pk_fma_f32 v[172:173], v[172:173], v[190:191], v[192:193]
	v_lshlrev_b32_e32 v190, 16, v147
	v_and_b32_e32 v191, 0xffff0000, v147
	v_lshlrev_b32_e32 v192, 16, v163
	v_and_b32_e32 v193, 0xffff0000, v163
	v_pk_fma_f32 v[174:175], v[174:175], v[190:191], v[192:193]
	v_lshlrev_b32_e32 v190, 16, v148
	v_and_b32_e32 v191, 0xffff0000, v148
	v_lshlrev_b32_e32 v192, 16, v164
	v_and_b32_e32 v193, 0xffff0000, v164
	v_pk_fma_f32 v[176:177], v[176:177], v[190:191], v[192:193]
	v_lshlrev_b32_e32 v190, 16, v149
	v_and_b32_e32 v191, 0xffff0000, v149
	v_lshlrev_b32_e32 v192, 16, v165
	v_and_b32_e32 v193, 0xffff0000, v165
	v_pk_fma_f32 v[178:179], v[178:179], v[190:191], v[192:193]
	v_cvt_pk_bf16_f32 v186, v172, v173
	v_cvt_pk_bf16_f32 v187, v174, v175
	v_cvt_pk_bf16_f32 v188, v176, v177
	v_cvt_pk_bf16_f32 v189, v178, v179
	global_store_dwordx4 v[202:203], v[186:189], off
	s_nop 1
	v_lshl_add_u64 v[202:203], v[202:203], 0, s[38:39]
	global_load_dwordx4 v[146:149], v[194:195], off
	global_load_dwordx4 v[162:165], v[198:199], off
	v_lshl_add_u64 v[194:195], v[194:195], 0, s[92:93]
	v_lshl_add_u64 v[198:199], v[198:199], 0, s[38:39]
	ds_read_b128 v[172:175], v0 offset:25344
	ds_read_b128 v[176:179], v0 offset:25360
	s_waitcnt vmcnt(9) lgkmcnt(0)
; DI unsigned pk2(float a, float b) { f32x2 v = {a, b}; bf2_t r = __builtin_convertvector(v, bf2_t); return __builtin_bit_cast(unsigned, r); }
; DI float bf_lo(unsigned u) { return __uint_as_float(u << 16); }
; DI float bf_hi(unsigned u) { return __uint_as_float(u & 0xffff0000u); }
; DI void gemm_up_pass_big(const bf16_t* Y, const bf16_t* W, const bf16_t* __restrict__ GBR, int gcol0, bf16_t* __restrict__ MG, bool first,
;                          int mt, int nt, char* smem) {
;     ...
; #pragma unroll 2
;     for (int ps = 0; ps < 8; ++ps) {
;       const int row = ps * 16 + r;
;       const float4 a0 = *(const float4*)(st + row * 132 + ch * 8), a1 = *(const float4*)(st + row * 132 + ch * 8 + 4);
;       const size_t grow = (size_t)(m0 + h * 128 + row);
;       const u32x4 gv = *(const u32x4*)(GBR + grow * 2048 + gcol0 + n0 + ch * 8);
;       float v[8];
;       v[0] = bf_lo(gv.x) * a0.x; v[1] = bf_hi(gv.x) * a0.y; v[2] = bf_lo(gv.y) * a0.z; v[3] = bf_hi(gv.y) * a0.w;
;       v[4] = bf_lo(gv.z) * a1.x; v[5] = bf_hi(gv.z) * a1.y; v[6] = bf_lo(gv.w) * a1.z; v[7] = bf_hi(gv.w) * a1.w;
;       bf16_t* mp = MG + grow * 1024 + n0 + ch * 8;
;       if (!first) {
;         const u32x4 pv = *(const u32x4*)mp;
;         v[0] += bf_lo(pv.x); v[1] += bf_hi(pv.x); v[2] += bf_lo(pv.y); v[3] += bf_hi(pv.y);
;         v[4] += bf_lo(pv.z); v[5] += bf_hi(pv.z); v[6] += bf_lo(pv.w); v[7] += bf_hi(pv.w);
;       }
;       u32x4 ov; ov.x = pk2(v[0], v[1]); ov.y = pk2(v[2], v[3]); ov.z = pk2(v[4], v[5]); ov.w = pk2(v[6], v[7]);
;       *(u32x4*)mp = ov;
;     }
;     __syncthreads();
	v_lshlrev_b32_e32 v190, 16, v150
	v_and_b32_e32 v191, 0xffff0000, v150
	v_lshlrev_b32_e32 v192, 16, v166
	v_and_b32_e32 v193, 0xffff0000, v166
	v_pk_fma_f32 v[172:173], v[172:173], v[190:191], v[192:193]
	v_lshlrev_b32_e32 v190, 16, v151
	v_and_b32_e32 v191, 0xffff0000, v151
	v_lshlrev_b32_e32 v192, 16, v167
	v_and_b32_e32 v193, 0xffff0000, v167
	v_pk_fma_f32 v[174:175], v[174:175], v[190:191], v[192:193]
	v_lshlrev_b32_e32 v190, 16, v152
	v_and_b32_e32 v191, 0xffff0000, v152
	v_lshlrev_b32_e32 v192, 16, v168
	v_and_b32_e32 v193, 0xffff0000, v168
	v_pk_fma_f32 v[176:177], v[176:177], v[190:191], v[192:193]
	v_lshlrev_b32_e32 v190, 16, v153
	v_and_b32_e32 v191, 0xffff0000, v153
	v_lshlrev_b32_e32 v192, 16, v169
	v_and_b32_e32 v193, 0xffff0000, v169
	v_pk_fma_f32 v[178:179], v[178:179], v[190:191], v[192:193]
	v_cvt_pk_bf16_f32 v186, v172, v173
	v_cvt_pk_bf16_f32 v187, v174, v175
	v_cvt_pk_bf16_f32 v188, v176, v177
	v_cvt_pk_bf16_f32 v189, v178, v179
	global_store_dwordx4 v[204:205], v[186:189], off
	s_nop 1
	v_lshl_add_u64 v[204:205], v[204:205], 0, s[38:39]
	global_load_dwordx4 v[150:153], v[196:197], off
	global_load_dwordx4 v[166:169], v[200:201], off
	v_lshl_add_u64 v[196:197], v[196:197], 0, s[92:93]
	v_lshl_add_u64 v[200:201], v[200:201], 0, s[38:39]
	ds_read_b128 v[172:175], v0 offset:33792
	ds_read_b128 v[176:179], v0 offset:33808
	s_waitcnt vmcnt(9) lgkmcnt(0)
	v_lshlrev_b32_e32 v190, 16, v138
	v_and_b32_e32 v191, 0xffff0000, v138
	v_lshlrev_b32_e32 v192, 16, v154
	v_and_b32_e32 v193, 0xffff0000, v154
	v_pk_fma_f32 v[172:173], v[172:173], v[190:191], v[192:193]
	v_lshlrev_b32_e32 v190, 16, v139
	v_and_b32_e32 v191, 0xffff0000, v139
	v_lshlrev_b32_e32 v192, 16, v155
	v_and_b32_e32 v193, 0xffff0000, v155
	v_pk_fma_f32 v[174:175], v[174:175], v[190:191], v[192:193]
	v_lshlrev_b32_e32 v190, 16, v140
	v_and_b32_e32 v191, 0xffff0000, v140
	v_lshlrev_b32_e32 v192, 16, v156
	v_and_b32_e32 v193, 0xffff0000, v156
	v_pk_fma_f32 v[176:177], v[176:177], v[190:191], v[192:193]
	v_lshlrev_b32_e32 v190, 16, v141
	v_and_b32_e32 v191, 0xffff0000, v141
	v_lshlrev_b32_e32 v192, 16, v157
	v_and_b32_e32 v193, 0xffff0000, v157
	v_pk_fma_f32 v[178:179], v[178:179], v[190:191], v[192:193]
	v_cvt_pk_bf16_f32 v186, v172, v173
	v_cvt_pk_bf16_f32 v187, v174, v175
	v_cvt_pk_bf16_f32 v188, v176, v177
	v_cvt_pk_bf16_f32 v189, v178, v179
	global_store_dwordx4 v[202:203], v[186:189], off
	s_nop 1
	v_lshl_add_u64 v[202:203], v[202:203], 0, s[38:39]
	ds_read_b128 v[172:175], v0 offset:42240
	ds_read_b128 v[176:179], v0 offset:42256
	s_waitcnt vmcnt(7) lgkmcnt(0)
	v_lshlrev_b32_e32 v190, 16, v142
	v_and_b32_e32 v191, 0xffff0000, v142
	v_lshlrev_b32_e32 v192, 16, v158
	v_and_b32_e32 v193, 0xffff0000, v158
	v_pk_fma_f32 v[172:173], v[172:173], v[190:191], v[192:193]
	v_lshlrev_b32_e32 v190, 16, v143
	v_and_b32_e32 v191, 0xffff0000, v143
	v_lshlrev_b32_e32 v192, 16, v159
	v_and_b32_e32 v193, 0xffff0000, v159
	v_pk_fma_f32 v[174:175], v[174:175], v[190:191], v[192:193]
	v_lshlrev_b32_e32 v190, 16, v144
	v_and_b32_e32 v191, 0xffff0000, v144
	v_lshlrev_b32_e32 v192, 16, v160
	v_and_b32_e32 v193, 0xffff0000, v160
	v_pk_fma_f32 v[176:177], v[176:177], v[190:191], v[192:193]
	v_lshlrev_b32_e32 v190, 16, v145
	v_and_b32_e32 v191, 0xffff0000, v145
	v_lshlrev_b32_e32 v192, 16, v161
	v_and_b32_e32 v193, 0xffff0000, v161
	v_pk_fma_f32 v[178:179], v[178:179], v[190:191], v[192:193]
	v_cvt_pk_bf16_f32 v186, v172, v173
	v_cvt_pk_bf16_f32 v187, v174, v175
	v_cvt_pk_bf16_f32 v188, v176, v177
	v_cvt_pk_bf16_f32 v189, v178, v179
	global_store_dwordx4 v[204:205], v[186:189], off
	s_nop 1
	v_lshl_add_u64 v[204:205], v[204:205], 0, s[38:39]
	ds_read_b128 v[172:175], v0 offset:50688
	ds_read_b128 v[176:179], v0 offset:50704
	s_waitcnt vmcnt(5) lgkmcnt(0)
	v_lshlrev_b32_e32 v190, 16, v146
	v_and_b32_e32 v191, 0xffff0000, v146
	v_lshlrev_b32_e32 v192, 16, v162
	v_and_b32_e32 v193, 0xffff0000, v162
	v_pk_fma_f32 v[172:173], v[172:173], v[190:191], v[192:193]
	v_lshlrev_b32_e32 v190, 16, v147
	v_and_b32_e32 v191, 0xffff0000, v147
	v_lshlrev_b32_e32 v192, 16, v163
	v_and_b32_e32 v193, 0xffff0000, v163
	v_pk_fma_f32 v[174:175], v[174:175], v[190:191], v[192:193]
	v_lshlrev_b32_e32 v190, 16, v148
	v_and_b32_e32 v191, 0xffff0000, v148
	v_lshlrev_b32_e32 v192, 16, v164
	v_and_b32_e32 v193, 0xffff0000, v164
	v_pk_fma_f32 v[176:177], v[176:177], v[190:191], v[192:193]
	v_lshlrev_b32_e32 v190, 16, v149
	v_and_b32_e32 v191, 0xffff0000, v149
	v_lshlrev_b32_e32 v192, 16, v165
	v_and_b32_e32 v193, 0xffff0000, v165
	v_pk_fma_f32 v[178:179], v[178:179], v[190:191], v[192:193]
	v_cvt_pk_bf16_f32 v186, v172, v173
	v_cvt_pk_bf16_f32 v187, v174, v175
	v_cvt_pk_bf16_f32 v188, v176, v177
	v_cvt_pk_bf16_f32 v189, v178, v179
	global_store_dwordx4 v[202:203], v[186:189], off
	s_nop 1
	v_lshl_add_u64 v[202:203], v[202:203], 0, s[38:39]
	ds_read_b128 v[172:175], v0 offset:59136
	ds_read_b128 v[176:179], v0 offset:59152
	s_waitcnt vmcnt(3) lgkmcnt(0)
	v_lshlrev_b32_e32 v190, 16, v150
	v_and_b32_e32 v191, 0xffff0000, v150
	v_lshlrev_b32_e32 v192, 16, v166
	v_and_b32_e32 v193, 0xffff0000, v166
	v_pk_fma_f32 v[172:173], v[172:173], v[190:191], v[192:193]
	v_lshlrev_b32_e32 v190, 16, v151
	v_and_b32_e32 v191, 0xffff0000, v151
	v_lshlrev_b32_e32 v192, 16, v167
	v_and_b32_e32 v193, 0xffff0000, v167
	v_pk_fma_f32 v[174:175], v[174:175], v[190:191], v[192:193]
	v_lshlrev_b32_e32 v190, 16, v152
	v_and_b32_e32 v191, 0xffff0000, v152
	v_lshlrev_b32_e32 v192, 16, v168
	v_and_b32_e32 v193, 0xffff0000, v168
	v_pk_fma_f32 v[176:177], v[176:177], v[190:191], v[192:193]
	v_lshlrev_b32_e32 v190, 16, v153
	v_and_b32_e32 v191, 0xffff0000, v153
	v_lshlrev_b32_e32 v192, 16, v169
	v_and_b32_e32 v193, 0xffff0000, v169
	v_pk_fma_f32 v[178:179], v[178:179], v[190:191], v[192:193]
	v_cvt_pk_bf16_f32 v186, v172, v173
	v_cvt_pk_bf16_f32 v187, v174, v175
	v_cvt_pk_bf16_f32 v188, v176, v177
	v_cvt_pk_bf16_f32 v189, v178, v179
	global_store_dwordx4 v[204:205], v[186:189], off
	s_nop 1
	v_lshl_add_u64 v[204:205], v[204:205], 0, s[38:39]
	v_mov_b32_e32 v0, v216
	s_barrier
; DI int crow(int i, int h) { return (i & 3) + 8 * (i >> 2) + 4 * h; }
; DI void stage_half(float* st, const f32x16 (&acc)[4][2], int h, int tid) {
;   const int lane = tid & 63, w = tid >> 6, wm = w >> 1, wn = w & 1, c = lane & 31, half = lane >> 5;
;   if (wm == h) {
; #pragma unroll
;     for (int mf = 0; mf < 4; ++mf)
; #pragma unroll
;       for (int nf = 0; nf < 2; ++nf)
; #pragma unroll
;         for (int i = 0; i < 16; ++i) st[(mf * 32 + crow(i, half)) * 132 + wn * 64 + nf * 32 + c] = acc[mf][nf][i];
;   }
; }
	s_nop 0
	v_and_b32_e32 v130, 0xffffff80, v0
	v_cmp_eq_u32_e32 vcc, s31, v130
	s_and_saveexec_b64 s[42:43], vcc
	s_cbranch_execz .LBB0_1058
	v_lshrrev_b32_e32 v130, 3, v0
	v_and_b32_e32 v130, 4, v130
	v_and_b32_e32 v131, 0x5f, v0
	v_mul_u32_u24_e32 v130, 0x210, v130
	v_lshl_add_u32 v130, v131, 2, v130
	ds_write2_b32 v130, v98, v114 offset1:32
	ds_write2_b32 v130, v99, v115 offset0:132 offset1:164
	v_add_u32_e32 v98, 0x400, v130
	ds_write2_b32 v98, v100, v116 offset0:8 offset1:40
	ds_write2_b32 v98, v101, v117 offset0:140 offset1:172
	v_add_u32_e32 v98, 0x1000, v130
	ds_write2_b32 v98, v102, v118 offset0:32 offset1:64
	ds_write2_b32 v98, v103, v119 offset0:164 offset1:196
	v_add_u32_e32 v98, 0x1400, v130
	ds_write2_b32 v98, v104, v120 offset0:40 offset1:72
	ds_write2_b32 v98, v105, v121 offset0:172 offset1:204
	v_add_u32_e32 v98, 0x2000, v130
	ds_write2_b32 v98, v106, v122 offset0:64 offset1:96
	ds_write2_b32 v98, v107, v123 offset0:196 offset1:228
	v_add_u32_e32 v98, 0x2400, v130
	ds_write2_b32 v98, v108, v124 offset0:72 offset1:104
	ds_write2_b32 v98, v109, v125 offset0:204 offset1:236
	v_add_u32_e32 v98, 0x3000, v130
	ds_write2_b32 v98, v110, v126 offset0:96 offset1:128
	v_add_u32_e32 v98, 0x3200, v130
	ds_write2_b32 v98, v111, v127 offset0:100 offset1:132
	v_add_u32_e32 v98, 0x3400, v130
	ds_write2_b32 v98, v112, v128 offset0:104 offset1:136
	v_add_u32_e32 v98, 0x3600, v130
	ds_write2_b32 v98, v113, v129 offset0:108 offset1:140
	v_add_u32_e32 v98, 0x4000, v130
	ds_write2_b32 v98, v66, v82 offset0:128 offset1:160
	v_add_u32_e32 v66, 0x4400, v130
	ds_write2_b32 v66, v67, v83 offset0:4 offset1:36
	ds_write2_b32 v66, v68, v84 offset0:136 offset1:168
	v_add_u32_e32 v66, 0x4800, v130
	ds_write2_b32 v66, v69, v85 offset0:12 offset1:44
	v_add_u32_e32 v66, 0x5000, v130
	ds_write2_b32 v66, v70, v86 offset0:160 offset1:192
	v_add_u32_e32 v66, 0x5400, v130
	ds_write2_b32 v66, v71, v87 offset0:36 offset1:68
	ds_write2_b32 v66, v72, v88 offset0:168 offset1:200
	v_add_u32_e32 v66, 0x5800, v130
	ds_write2_b32 v66, v73, v89 offset0:44 offset1:76
	v_add_u32_e32 v66, 0x6000, v130
	ds_write2_b32 v66, v74, v90 offset0:192 offset1:224
	v_add_u32_e32 v66, 0x6400, v130
	ds_write2_b32 v66, v75, v91 offset0:68 offset1:100
	ds_write2_b32 v66, v76, v92 offset0:200 offset1:232
	v_add_u32_e32 v66, 0x6800, v130
	ds_write2_b32 v66, v77, v93 offset0:76 offset1:108
	v_add_u32_e32 v66, 0x7200, v130
	ds_write2_b32 v66, v78, v94 offset0:96 offset1:128
	v_add_u32_e32 v66, 0x7400, v130
	ds_write2_b32 v66, v79, v95 offset0:100 offset1:132
	v_add_u32_e32 v66, 0x7600, v130
	ds_write2_b32 v66, v80, v96 offset0:104 offset1:136
	v_add_u32_e32 v66, 0x7800, v130
	ds_write2_b32 v66, v81, v97 offset0:108 offset1:140
	v_add_u32_e32 v66, 0x8400, v130
	ds_write2_b32 v66, v34, v50 offset1:32
	ds_write2_b32 v66, v35, v51 offset0:132 offset1:164
	v_add_u32_e32 v34, 0x8800, v130
	ds_write2_b32 v34, v36, v52 offset0:8 offset1:40
	ds_write2_b32 v34, v37, v53 offset0:140 offset1:172
	v_add_u32_e32 v34, 0x9400, v130
	ds_write2_b32 v34, v38, v54 offset0:32 offset1:64
	ds_write2_b32 v34, v39, v55 offset0:164 offset1:196
	v_add_u32_e32 v34, 0x9800, v130
	ds_write2_b32 v34, v40, v56 offset0:40 offset1:72
	ds_write2_b32 v34, v41, v57 offset0:172 offset1:204
	v_add_u32_e32 v34, 0xa400, v130
	ds_write2_b32 v34, v42, v58 offset0:64 offset1:96
	ds_write2_b32 v34, v43, v59 offset0:196 offset1:228
	v_add_u32_e32 v34, 0xa800, v130
	ds_write2_b32 v34, v44, v60 offset0:72 offset1:104
	ds_write2_b32 v34, v45, v61 offset0:204 offset1:236
	v_add_u32_e32 v34, 0xb400, v130
	ds_write2_b32 v34, v46, v62 offset0:96 offset1:128
	v_add_u32_e32 v34, 0xb600, v130
	ds_write2_b32 v34, v47, v63 offset0:100 offset1:132
	v_add_u32_e32 v34, 0xb800, v130
	ds_write2_b32 v34, v48, v64 offset0:104 offset1:136
	v_add_u32_e32 v34, 0xba00, v130
	ds_write2_b32 v34, v49, v65 offset0:108 offset1:140
	v_add_u32_e32 v34, 0xc400, v130
	ds_write2_b32 v34, v2, v18 offset0:128 offset1:160
	v_add_u32_e32 v2, 0xc800, v130
	ds_write2_b32 v2, v3, v19 offset0:4 offset1:36
	ds_write2_b32 v2, v4, v20 offset0:136 offset1:168
	v_add_u32_e32 v2, 0xcc00, v130
	ds_write2_b32 v2, v5, v21 offset0:12 offset1:44
	v_add_u32_e32 v2, 0xd400, v130
	ds_write2_b32 v2, v6, v22 offset0:160 offset1:192
	v_add_u32_e32 v2, 0xd800, v130
	ds_write2_b32 v2, v7, v23 offset0:36 offset1:68
	ds_write2_b32 v2, v8, v24 offset0:168 offset1:200
	v_add_u32_e32 v2, 0xdc00, v130
	ds_write2_b32 v2, v9, v25 offset0:44 offset1:76
	v_add_u32_e32 v2, 0xe400, v130
	ds_write2_b32 v2, v10, v26 offset0:192 offset1:224
	v_add_u32_e32 v2, 0xe800, v130
	ds_write2_b32 v2, v11, v27 offset0:68 offset1:100
	ds_write2_b32 v2, v12, v28 offset0:200 offset1:232
	v_add_u32_e32 v2, 0xec00, v130
	ds_write2_b32 v2, v13, v29 offset0:76 offset1:108
	v_add_u32_e32 v2, 0xf600, v130
	ds_write2_b32 v2, v14, v30 offset0:96 offset1:128
	v_add_u32_e32 v2, 0xf800, v130
	ds_write2_b32 v2, v15, v31 offset0:100 offset1:132
	v_add_u32_e32 v2, 0xfa00, v130
	ds_write2_b32 v2, v16, v32 offset0:104 offset1:136
	v_add_u32_e32 v2, 0xfc00, v130
	ds_write2_b32 v2, v17, v33 offset0:108 offset1:140

; DI unsigned pk2(float a, float b) { f32x2 v = {a, b}; bf2_t r = __builtin_convertvector(v, bf2_t); return __builtin_bit_cast(unsigned, r); }
; DI float bf_lo(unsigned u) { return __uint_as_float(u << 16); }
; DI float bf_hi(unsigned u) { return __uint_as_float(u & 0xffff0000u); }
; DI void gemm_up_pass_big(const bf16_t* Y, const bf16_t* W, const bf16_t* __restrict__ GBR, int gcol0, bf16_t* __restrict__ MG, bool first,
;                          int mt, int nt, char* smem) {
;     ...
;     const int r = tid >> 4, ch = tid & 15;
; #pragma unroll 2
;     for (int ps = 0; ps < 8; ++ps) {
;       const int row = ps * 16 + r;
;       const float4 a0 = *(const float4*)(st + row * 132 + ch * 8), a1 = *(const float4*)(st + row * 132 + ch * 8 + 4);
;       const size_t grow = (size_t)(m0 + h * 128 + row);
;       const u32x4 gv = *(const u32x4*)(GBR + grow * 2048 + gcol0 + n0 + ch * 8);
;       float v[8];
;       v[0] = bf_lo(gv.x) * a0.x; v[1] = bf_hi(gv.x) * a0.y; v[2] = bf_lo(gv.y) * a0.z; v[3] = bf_hi(gv.y) * a0.w;
;       v[4] = bf_lo(gv.z) * a1.x; v[5] = bf_hi(gv.z) * a1.y; v[6] = bf_lo(gv.w) * a1.z; v[7] = bf_hi(gv.w) * a1.w;
;       bf16_t* mp = MG + grow * 1024 + n0 + ch * 8;
;       if (!first) {
;         const u32x4 pv = *(const u32x4*)mp;
;         v[0] += bf_lo(pv.x); v[1] += bf_hi(pv.x); v[2] += bf_lo(pv.y); v[3] += bf_hi(pv.y);
;         v[4] += bf_lo(pv.z); v[5] += bf_hi(pv.z); v[6] += bf_lo(pv.w); v[7] += bf_hi(pv.w);
;       }
;       u32x4 ov; ov.x = pk2(v[0], v[1]); ov.y = pk2(v[2], v[3]); ov.z = pk2(v[4], v[5]); ov.w = pk2(v[6], v[7]);
;       *(u32x4*)mp = ov;
;     }
.LBB0_1059:
	v_lshl_add_u64 v[194:195], v[8:9], 0, s[28:29]
	v_lshl_add_u64 v[196:197], v[4:5], 0, s[28:29]
	v_lshl_add_u64 v[202:203], v[6:7], 0, s[28:29]
	v_lshl_add_u64 v[204:205], v[2:3], 0, s[28:29]
	v_lshl_add_u64 v[198:199], v[6:7], 0, s[28:29]
	v_lshl_add_u64 v[200:201], v[2:3], 0, s[28:29]
	global_load_dwordx4 v[138:141], v[194:195], off
	global_load_dwordx4 v[154:157], v[198:199], off
	v_lshl_add_u64 v[194:195], v[194:195], 0, s[92:93]
	v_lshl_add_u64 v[198:199], v[198:199], 0, s[38:39]
	global_load_dwordx4 v[142:145], v[196:197], off
	global_load_dwordx4 v[158:161], v[200:201], off
	v_lshl_add_u64 v[196:197], v[196:197], 0, s[92:93]
	v_lshl_add_u64 v[200:201], v[200:201], 0, s[38:39]
	global_load_dwordx4 v[146:149], v[194:195], off
	global_load_dwordx4 v[162:165], v[198:199], off
	v_lshl_add_u64 v[194:195], v[194:195], 0, s[92:93]
	v_lshl_add_u64 v[198:199], v[198:199], 0, s[38:39]
	global_load_dwordx4 v[150:153], v[196:197], off
	global_load_dwordx4 v[166:169], v[200:201], off
	v_lshl_add_u64 v[196:197], v[196:197], 0, s[92:93]
	v_lshl_add_u64 v[200:201], v[200:201], 0, s[38:39]
	ds_read_b128 v[172:175], v0 offset:0
	ds_read_b128 v[176:179], v0 offset:16
	s_waitcnt vmcnt(6) lgkmcnt(0)
	v_lshlrev_b32_e32 v190, 16, v138
	v_and_b32_e32 v191, 0xffff0000, v138
	v_lshlrev_b32_e32 v192, 16, v154
	v_and_b32_e32 v193, 0xffff0000, v154
	v_pk_fma_f32 v[172:173], v[172:173], v[190:191], v[192:193]
	v_lshlrev_b32_e32 v190, 16, v139
	v_and_b32_e32 v191, 0xffff0000, v139
	v_lshlrev_b32_e32 v192, 16, v155
	v_and_b32_e32 v193, 0xffff0000, v155
	v_pk_fma_f32 v[174:175], v[174:175], v[190:191], v[192:193]
	v_lshlrev_b32_e32 v190, 16, v140
	v_and_b32_e32 v191, 0xffff0000, v140
	v_lshlrev_b32_e32 v192, 16, v156
	v_and_b32_e32 v193, 0xffff0000, v156
	v_pk_fma_f32 v[176:177], v[176:177], v[190:191], v[192:193]
	v_lshlrev_b32_e32 v190, 16, v141
	v_and_b32_e32 v191, 0xffff0000, v141
	v_lshlrev_b32_e32 v192, 16, v157
	v_and_b32_e32 v193, 0xffff0000, v157
	v_pk_fma_f32 v[178:179], v[178:179], v[190:191], v[192:193]
	v_cvt_pk_bf16_f32 v186, v172, v173
	v_cvt_pk_bf16_f32 v187, v174, v175
	v_cvt_pk_bf16_f32 v188, v176, v177
	v_cvt_pk_bf16_f32 v189, v178, v179
	global_store_dwordx4 v[202:203], v[186:189], off
	s_nop 1
	v_lshl_add_u64 v[202:203], v[202:203], 0, s[38:39]
	global_load_dwordx4 v[138:141], v[194:195], off
	global_load_dwordx4 v[154:157], v[198:199], off
	v_lshl_add_u64 v[194:195], v[194:195], 0, s[92:93]
	v_lshl_add_u64 v[198:199], v[198:199], 0, s[38:39]
	ds_read_b128 v[172:175], v0 offset:8448
	ds_read_b128 v[176:179], v0 offset:8464
	s_waitcnt vmcnt(7) lgkmcnt(0)
	v_lshlrev_b32_e32 v190, 16, v142
	v_and_b32_e32 v191, 0xffff0000, v142
	v_lshlrev_b32_e32 v192, 16, v158
	v_and_b32_e32 v193, 0xffff0000, v158
	v_pk_fma_f32 v[172:173], v[172:173], v[190:191], v[192:193]
	v_lshlrev_b32_e32 v190, 16, v143
	v_and_b32_e32 v191, 0xffff0000, v143
	v_lshlrev_b32_e32 v192, 16, v159
	v_and_b32_e32 v193, 0xffff0000, v159
	v_pk_fma_f32 v[174:175], v[174:175], v[190:191], v[192:193]
	v_lshlrev_b32_e32 v190, 16, v144
	v_and_b32_e32 v191, 0xffff0000, v144
	v_lshlrev_b32_e32 v192, 16, v160
	v_and_b32_e32 v193, 0xffff0000, v160
	v_pk_fma_f32 v[176:177], v[176:177], v[190:191], v[192:193]
	v_lshlrev_b32_e32 v190, 16, v145
	v_and_b32_e32 v191, 0xffff0000, v145
	v_lshlrev_b32_e32 v192, 16, v161
	v_and_b32_e32 v193, 0xffff0000, v161
	v_pk_fma_f32 v[178:179], v[178:179], v[190:191], v[192:193]
	v_cvt_pk_bf16_f32 v186, v172, v173
	v_cvt_pk_bf16_f32 v187, v174, v175
	v_cvt_pk_bf16_f32 v188, v176, v177
	v_cvt_pk_bf16_f32 v189, v178, v179
	global_store_dwordx4 v[204:205], v[186:189], off
	s_nop 1
	v_lshl_add_u64 v[204:205], v[204:205], 0, s[38:39]
	global_load_dwordx4 v[142:145], v[196:197], off
	global_load_dwordx4 v[158:161], v[200:201], off
	v_lshl_add_u64 v[196:197], v[196:197], 0, s[92:93]
	v_lshl_add_u64 v[200:201], v[200:201], 0, s[38:39]
	ds_read_b128 v[172:175], v0 offset:16896
	ds_read_b128 v[176:179], v0 offset:16912
	s_waitcnt vmcnt(8) lgkmcnt(0)
	v_lshlrev_b32_e32 v190, 16, v146
	v_and_b32_e32 v191, 0xffff0000, v146
	v_lshlrev_b32_e32 v192, 16, v162
	v_and_b32_e32 v193, 0xffff0000, v162
	v_pk_fma_f32 v[172:173], v[172:173], v[190:191], v[192:193]
	v_lshlrev_b32_e32 v190, 16, v147
	v_and_b32_e32 v191, 0xffff0000, v147
	v_lshlrev_b32_e32 v192, 16, v163
	v_and_b32_e32 v193, 0xffff0000, v163
	v_pk_fma_f32 v[174:175], v[174:175], v[190:191], v[192:193]
	v_lshlrev_b32_e32 v190, 16, v148
	v_and_b32_e32 v191, 0xffff0000, v148
	v_lshlrev_b32_e32 v192, 16, v164
	v_and_b32_e32 v193, 0xffff0000, v164
	v_pk_fma_f32 v[176:177], v[176:177], v[190:191], v[192:193]
	v_lshlrev_b32_e32 v190, 16, v149
	v_and_b32_e32 v191, 0xffff0000, v149
	v_lshlrev_b32_e32 v192, 16, v165
	v_and_b32_e32 v193, 0xffff0000, v165
	v_pk_fma_f32 v[178:179], v[178:179], v[190:191], v[192:193]
	v_cvt_pk_bf16_f32 v186, v172, v173
	v_cvt_pk_bf16_f32 v187, v174, v175
	v_cvt_pk_bf16_f32 v188, v176, v177
	v_cvt_pk_bf16_f32 v189, v178, v179
	global_store_dwordx4 v[202:203], v[186:189], off
	s_nop 1
	v_lshl_add_u64 v[202:203], v[202:203], 0, s[38:39]
	global_load_dwordx4 v[146:149], v[194:195], off
	global_load_dwordx4 v[162:165], v[198:199], off
	v_lshl_add_u64 v[194:195], v[194:195], 0, s[92:93]
	v_lshl_add_u64 v[198:199], v[198:199], 0, s[38:39]
	ds_read_b128 v[172:175], v0 offset:25344
	ds_read_b128 v[176:179], v0 offset:25360
	s_waitcnt vmcnt(9) lgkmcnt(0)
; DI unsigned pk2(float a, float b) { f32x2 v = {a, b}; bf2_t r = __builtin_convertvector(v, bf2_t); return __builtin_bit_cast(unsigned, r); }
; DI float bf_lo(unsigned u) { return __uint_as_float(u << 16); }
; DI float bf_hi(unsigned u) { return __uint_as_float(u & 0xffff0000u); }
; DI void gemm_up_pass_big(const bf16_t* Y, const bf16_t* W, const bf16_t* __restrict__ GBR, int gcol0, bf16_t* __restrict__ MG, bool first,
;                          int mt, int nt, char* smem) {
;     ...
; #pragma unroll 2
;     for (int ps = 0; ps < 8; ++ps) {
;       const int row = ps * 16 + r;
;       const float4 a0 = *(const float4*)(st + row * 132 + ch * 8), a1 = *(const float4*)(st + row * 132 + ch * 8 + 4);
;       const size_t grow = (size_t)(m0 + h * 128 + row);
;       const u32x4 gv = *(const u32x4*)(GBR + grow * 2048 + gcol0 + n0 + ch * 8);
;       float v[8];
;       v[0] = bf_lo(gv.x) * a0.x; v[1] = bf_hi(gv.x) * a0.y; v[2] = bf_lo(gv.y) * a0.z; v[3] = bf_hi(gv.y) * a0.w;
;       v[4] = bf_lo(gv.z) * a1.x; v[5] = bf_hi(gv.z) * a1.y; v[6] = bf_lo(gv.w) * a1.z; v[7] = bf_hi(gv.w) * a1.w;
;       bf16_t* mp = MG + grow * 1024 + n0 + ch * 8;
;       if (!first) {
;         const u32x4 pv = *(const u32x4*)mp;
;         v[0] += bf_lo(pv.x); v[1] += bf_hi(pv.x); v[2] += bf_lo(pv.y); v[3] += bf_hi(pv.y);
;         v[4] += bf_lo(pv.z); v[5] += bf_hi(pv.z); v[6] += bf_lo(pv.w); v[7] += bf_hi(pv.w);
;       }
;       u32x4 ov; ov.x = pk2(v[0], v[1]); ov.y = pk2(v[2], v[3]); ov.z = pk2(v[4], v[5]); ov.w = pk2(v[6], v[7]);
;       *(u32x4*)mp = ov;
;     }
;     __syncthreads();
	v_lshlrev_b32_e32 v190, 16, v150
	v_and_b32_e32 v191, 0xffff0000, v150
	v_lshlrev_b32_e32 v192, 16, v166
	v_and_b32_e32 v193, 0xffff0000, v166
	v_pk_fma_f32 v[172:173], v[172:173], v[190:191], v[192:193]
	v_lshlrev_b32_e32 v190, 16, v151
	v_and_b32_e32 v191, 0xffff0000, v151
	v_lshlrev_b32_e32 v192, 16, v167
	v_and_b32_e32 v193, 0xffff0000, v167
	v_pk_fma_f32 v[174:175], v[174:175], v[190:191], v[192:193]
	v_lshlrev_b32_e32 v190, 16, v152
	v_and_b32_e32 v191, 0xffff0000, v152
	v_lshlrev_b32_e32 v192, 16, v168
	v_and_b32_e32 v193, 0xffff0000, v168
	v_pk_fma_f32 v[176:177], v[176:177], v[190:191], v[192:193]
	v_lshlrev_b32_e32 v190, 16, v153
	v_and_b32_e32 v191, 0xffff0000, v153
	v_lshlrev_b32_e32 v192, 16, v169
	v_and_b32_e32 v193, 0xffff0000, v169
	v_pk_fma_f32 v[178:179], v[178:179], v[190:191], v[192:193]
	v_cvt_pk_bf16_f32 v186, v172, v173
	v_cvt_pk_bf16_f32 v187, v174, v175
	v_cvt_pk_bf16_f32 v188, v176, v177
	v_cvt_pk_bf16_f32 v189, v178, v179
	global_store_dwordx4 v[204:205], v[186:189], off
	s_nop 1
	v_lshl_add_u64 v[204:205], v[204:205], 0, s[38:39]
	global_load_dwordx4 v[150:153], v[196:197], off
	global_load_dwordx4 v[166:169], v[200:201], off
	v_lshl_add_u64 v[196:197], v[196:197], 0, s[92:93]
	v_lshl_add_u64 v[200:201], v[200:201], 0, s[38:39]
	ds_read_b128 v[172:175], v0 offset:33792
	ds_read_b128 v[176:179], v0 offset:33808
	s_waitcnt vmcnt(9) lgkmcnt(0)
	v_lshlrev_b32_e32 v190, 16, v138
	v_and_b32_e32 v191, 0xffff0000, v138
	v_lshlrev_b32_e32 v192, 16, v154
	v_and_b32_e32 v193, 0xffff0000, v154
	v_pk_fma_f32 v[172:173], v[172:173], v[190:191], v[192:193]
	v_lshlrev_b32_e32 v190, 16, v139
	v_and_b32_e32 v191, 0xffff0000, v139
	v_lshlrev_b32_e32 v192, 16, v155
	v_and_b32_e32 v193, 0xffff0000, v155
	v_pk_fma_f32 v[174:175], v[174:175], v[190:191], v[192:193]
	v_lshlrev_b32_e32 v190, 16, v140
	v_and_b32_e32 v191, 0xffff0000, v140
	v_lshlrev_b32_e32 v192, 16, v156
	v_and_b32_e32 v193, 0xffff0000, v156
	v_pk_fma_f32 v[176:177], v[176:177], v[190:191], v[192:193]
	v_lshlrev_b32_e32 v190, 16, v141
	v_and_b32_e32 v191, 0xffff0000, v141
	v_lshlrev_b32_e32 v192, 16, v157
	v_and_b32_e32 v193, 0xffff0000, v157
	v_pk_fma_f32 v[178:179], v[178:179], v[190:191], v[192:193]
	v_cvt_pk_bf16_f32 v186, v172, v173
	v_cvt_pk_bf16_f32 v187, v174, v175
	v_cvt_pk_bf16_f32 v188, v176, v177
	v_cvt_pk_bf16_f32 v189, v178, v179
	global_store_dwordx4 v[202:203], v[186:189], off
	s_nop 1
	v_lshl_add_u64 v[202:203], v[202:203], 0, s[38:39]
	ds_read_b128 v[172:175], v0 offset:42240
	ds_read_b128 v[176:179], v0 offset:42256
	s_waitcnt vmcnt(7) lgkmcnt(0)
	v_lshlrev_b32_e32 v190, 16, v142
	v_and_b32_e32 v191, 0xffff0000, v142
	v_lshlrev_b32_e32 v192, 16, v158
	v_and_b32_e32 v193, 0xffff0000, v158
	v_pk_fma_f32 v[172:173], v[172:173], v[190:191], v[192:193]
	v_lshlrev_b32_e32 v190, 16, v143
	v_and_b32_e32 v191, 0xffff0000, v143
	v_lshlrev_b32_e32 v192, 16, v159
	v_and_b32_e32 v193, 0xffff0000, v159
	v_pk_fma_f32 v[174:175], v[174:175], v[190:191], v[192:193]
	v_lshlrev_b32_e32 v190, 16, v144
	v_and_b32_e32 v191, 0xffff0000, v144
	v_lshlrev_b32_e32 v192, 16, v160
	v_and_b32_e32 v193, 0xffff0000, v160
	v_pk_fma_f32 v[176:177], v[176:177], v[190:191], v[192:193]
	v_lshlrev_b32_e32 v190, 16, v145
	v_and_b32_e32 v191, 0xffff0000, v145
	v_lshlrev_b32_e32 v192, 16, v161
	v_and_b32_e32 v193, 0xffff0000, v161
	v_pk_fma_f32 v[178:179], v[178:179], v[190:191], v[192:193]
	v_cvt_pk_bf16_f32 v186, v172, v173
	v_cvt_pk_bf16_f32 v187, v174, v175
	v_cvt_pk_bf16_f32 v188, v176, v177
	v_cvt_pk_bf16_f32 v189, v178, v179
	global_store_dwordx4 v[204:205], v[186:189], off
	s_nop 1
	v_lshl_add_u64 v[204:205], v[204:205], 0, s[38:39]
	ds_read_b128 v[172:175], v0 offset:50688
	ds_read_b128 v[176:179], v0 offset:50704
	s_waitcnt vmcnt(5) lgkmcnt(0)
	v_lshlrev_b32_e32 v190, 16, v146
	v_and_b32_e32 v191, 0xffff0000, v146
	v_lshlrev_b32_e32 v192, 16, v162
	v_and_b32_e32 v193, 0xffff0000, v162
	v_pk_fma_f32 v[172:173], v[172:173], v[190:191], v[192:193]
	v_lshlrev_b32_e32 v190, 16, v147
	v_and_b32_e32 v191, 0xffff0000, v147
	v_lshlrev_b32_e32 v192, 16, v163
	v_and_b32_e32 v193, 0xffff0000, v163
	v_pk_fma_f32 v[174:175], v[174:175], v[190:191], v[192:193]
	v_lshlrev_b32_e32 v190, 16, v148
	v_and_b32_e32 v191, 0xffff0000, v148
	v_lshlrev_b32_e32 v192, 16, v164
	v_and_b32_e32 v193, 0xffff0000, v164
	v_pk_fma_f32 v[176:177], v[176:177], v[190:191], v[192:193]
	v_lshlrev_b32_e32 v190, 16, v149
	v_and_b32_e32 v191, 0xffff0000, v149
	v_lshlrev_b32_e32 v192, 16, v165
	v_and_b32_e32 v193, 0xffff0000, v165
	v_pk_fma_f32 v[178:179], v[178:179], v[190:191], v[192:193]
	v_cvt_pk_bf16_f32 v186, v172, v173
	v_cvt_pk_bf16_f32 v187, v174, v175
	v_cvt_pk_bf16_f32 v188, v176, v177
	v_cvt_pk_bf16_f32 v189, v178, v179
	global_store_dwordx4 v[202:203], v[186:189], off
	s_nop 1
	v_lshl_add_u64 v[202:203], v[202:203], 0, s[38:39]
	ds_read_b128 v[172:175], v0 offset:59136
	ds_read_b128 v[176:179], v0 offset:59152
	s_waitcnt vmcnt(3) lgkmcnt(0)
	v_lshlrev_b32_e32 v190, 16, v150
	v_and_b32_e32 v191, 0xffff0000, v150
	v_lshlrev_b32_e32 v192, 16, v166
	v_and_b32_e32 v193, 0xffff0000, v166
	v_pk_fma_f32 v[172:173], v[172:173], v[190:191], v[192:193]
	v_lshlrev_b32_e32 v190, 16, v151
	v_and_b32_e32 v191, 0xffff0000, v151
	v_lshlrev_b32_e32 v192, 16, v167
	v_and_b32_e32 v193, 0xffff0000, v167
	v_pk_fma_f32 v[174:175], v[174:175], v[190:191], v[192:193]
	v_lshlrev_b32_e32 v190, 16, v152
	v_and_b32_e32 v191, 0xffff0000, v152
	v_lshlrev_b32_e32 v192, 16, v168
	v_and_b32_e32 v193, 0xffff0000, v168
	v_pk_fma_f32 v[176:177], v[176:177], v[190:191], v[192:193]
	v_lshlrev_b32_e32 v190, 16, v153
	v_and_b32_e32 v191, 0xffff0000, v153
	v_lshlrev_b32_e32 v192, 16, v169
	v_and_b32_e32 v193, 0xffff0000, v169
	v_pk_fma_f32 v[178:179], v[178:179], v[190:191], v[192:193]
	v_cvt_pk_bf16_f32 v186, v172, v173
	v_cvt_pk_bf16_f32 v187, v174, v175
	v_cvt_pk_bf16_f32 v188, v176, v177
	v_cvt_pk_bf16_f32 v189, v178, v179
	global_store_dwordx4 v[204:205], v[186:189], off
	s_nop 1
	v_lshl_add_u64 v[204:205], v[204:205], 0, s[38:39]
	s_barrier
	s_branch .LBB0_1042
